# shared-LDS attention with two 32-key steps per workgroup barrier (4-slot row ring, 4th slot in the bias-table area of other heads) + whole-line V epilogue
# baseline (speedup 1.0000x reference)
.LBB0_465:
	v_add_f32_e32 v1, v1, v4
	v_mul_f32_e32 v4, 0x4f800000, v1
	v_cmp_gt_f32_e32 vcc, s70, v1
	v_add_f32_e32 v2, v2, v3
	v_mul_f32_e32 v3, 0x4f800000, v2
	v_cndmask_b32_e32 v1, v1, v4, vcc
	v_sqrt_f32_e32 v4, v1
	s_mul_i32 s82, s82, 0x88000
	s_lshl_b32 s81, s7, 1
	s_mov_b32 s42, s26
	v_add_u32_e32 v9, -1, v4
	v_fma_f32 v10, -v9, v4, v1
	v_cmp_ge_f32_e64 s[0:1], 0, v10
	v_add_u32_e32 v10, 1, v4
	s_mov_b32 s43, s27
	v_cndmask_b32_e64 v9, v4, v9, s[0:1]
	v_fma_f32 v4, -v10, v4, v1
	v_cmp_lt_f32_e64 s[0:1], 0, v4
	s_or_b32 s20, s5, 1
	s_and_b32 s4, s4, 15
	v_cndmask_b32_e64 v4, v9, v10, s[0:1]
	v_mul_f32_e32 v9, 0x37800000, v4
	v_cndmask_b32_e32 v4, v4, v9, vcc
	v_cmp_gt_f32_e32 vcc, s70, v2
	v_cmp_class_f32_e64 s[0:1], v1, v237
	s_lshl_b32 s4, s4, 10
	v_cndmask_b32_e32 v2, v2, v3, vcc
	v_sqrt_f32_e32 v3, v2
	v_cndmask_b32_e64 v1, v4, v1, s[0:1]
	s_waitcnt lgkmcnt(8)
	v_fma_f32 v1, v227, v1, v228
	v_mov_b32_e32 v224, 0
	v_add_u32_e32 v4, -1, v3
	v_fma_f32 v9, -v4, v3, v2
	v_cmp_ge_f32_e64 s[0:1], 0, v9
	v_add_u32_e32 v9, 1, v3
	s_mov_b32 s92, 0
	v_cndmask_b32_e64 v4, v3, v4, s[0:1]
	v_fma_f32 v3, -v9, v3, v2
	v_cmp_lt_f32_e64 s[0:1], 0, v3
	s_add_i32 s83, s83, 20
	s_add_i32 s84, s75, 4
	v_cndmask_b32_e64 v3, v4, v9, s[0:1]
	v_mul_f32_e32 v4, 0x37800000, v3
	v_cndmask_b32_e32 v3, v3, v4, vcc
	v_add_f32_e32 v4, v5, v6
	v_mul_f32_e32 v5, 0x4f800000, v4
	v_cmp_gt_f32_e32 vcc, s70, v4
	v_cmp_class_f32_e64 s[0:1], v2, v237
	v_mov_b32_e32 v225, v224
	v_cndmask_b32_e32 v4, v4, v5, vcc
	v_sqrt_f32_e32 v5, v4
	v_cndmask_b32_e64 v2, v3, v2, s[0:1]
	v_fma_f32 v2, v227, v2, v228
	v_max3_f32 v1, v1, 0, v2
	v_add_u32_e32 v2, -1, v5
	v_fma_f32 v3, -v2, v5, v4
	v_cmp_ge_f32_e64 s[0:1], 0, v3
	v_add_u32_e32 v3, 1, v5
	v_mov_b32_e32 v222, v224
	v_cndmask_b32_e64 v2, v5, v2, s[0:1]
	v_fma_f32 v5, -v3, v5, v4
	v_cmp_lt_f32_e64 s[0:1], 0, v5
	v_mov_b32_e32 v223, v224
	s_nop 0
	v_cndmask_b32_e64 v2, v2, v3, s[0:1]
	v_mul_f32_e32 v3, 0x37800000, v2
	s_lshl_b32 s0, s8, 1
	v_cndmask_b32_e32 v2, v2, v3, vcc
	v_cmp_class_f32_e32 vcc, v4, v237
	v_add_f32_e32 v3, v7, v8
	s_add_i32 s0, s0, s82
	v_cndmask_b32_e32 v2, v2, v4, vcc
	v_mul_f32_e32 v4, 0x4f800000, v3
	v_cmp_gt_f32_e32 vcc, s70, v3
	s_add_i32 s7, s0, 0x44000
	s_add_i32 s1, s0, 0x4c800
	v_cndmask_b32_e32 v3, v3, v4, vcc
	s_add_i32 s9, s0, 0x8800
	v_sqrt_f32_e32 v52, v3
	v_fma_f32 v2, v227, v2, v228
	v_add_u32_e32 v53, -1, v52
	v_fma_f32 v54, -v53, v52, v3
	v_cmp_ge_f32_e64 s[0:1], 0, v54
	v_add_u32_e32 v54, 1, v52
	s_nop 0
	v_cndmask_b32_e64 v53, v52, v53, s[0:1]
	v_fma_f32 v52, -v54, v52, v3
	v_cmp_lt_f32_e64 s[0:1], 0, v52
	s_nop 1
	v_cndmask_b32_e64 v52, v53, v54, s[0:1]
	v_mul_f32_e32 v53, 0x37800000, v52
	v_cndmask_b32_e32 v52, v52, v53, vcc
	v_cmp_class_f32_e32 vcc, v3, v237
	s_nop 1
	v_cndmask_b32_e32 v3, v52, v3, vcc
	v_fma_f32 v3, v227, v3, v228
	v_max3_f32 v239, v1, v2, v3
	v_add_u32_e32 v1, s59, v232
	v_sub_u32_e32 v1, v229, v1
	v_add_u32_e32 v2, 15, v1
	v_cmp_gt_u32_e64 s[0:1], 16, v2
	v_add_u32_e32 v2, 14, v1
	v_cmp_gt_u32_e64 s[6:7], 16, v2
	v_add_u32_e32 v2, 13, v1
	v_cmp_gt_u32_e64 s[8:9], 16, v2
	v_add_u32_e32 v2, 12, v1
	v_cmp_gt_u32_e64 s[10:11], 16, v2
	v_add_u32_e32 v2, 11, v1
	v_cmp_gt_u32_e64 s[12:13], 16, v2
	v_add_u32_e32 v2, 10, v1
	v_cmp_gt_u32_e64 s[14:15], 16, v2
	v_add_u32_e32 v2, 9, v1
	v_add_u32_e32 v1, 8, v1
	v_cmp_gt_u32_e64 s[18:19], 16, v1
	v_sub_u32_e64 v1, s20, 4 clamp
	v_cmp_gt_u32_e64 s[16:17], 16, v2
	v_readfirstlane_b32 s20, v1
	s_min_u32 s85, s20, 56
	s_or_b32 s20, s5, 2
	v_sub_u32_e64 v1, s20, 4 clamp
	s_or_b32 s5, s5, 3
	v_readfirstlane_b32 s20, v1
	v_sub_u32_e64 v1, s5, 4 clamp
	s_min_u32 s87, s20, 56
	v_readfirstlane_b32 s5, v1
	s_min_u32 s89, s5, 56
	s_lshl_b32 s5, s75, 8
	s_lshl_b32 s20, s59, 2
	s_or_b32 s5, s5, s20
	v_lshrrev_b32_e32 v85, 4, v226
	v_and_b32_e32 v86, 15, v226
	v_lshlrev_b32_e32 v233, 9, v85
	v_lshl_add_u32 v233, v86, 4, v233
	v_lshlrev_b32_e32 v234, 4, v226
	s_lshl_b32 s97, s59, 3
	s_lshl_b32 s90, s59, 5
	s_mov_b32 s83, 0
	s_mov_b32 s77, 0x2000
	s_cmp_eq_u32 s64, 0
	s_cselect_b32 s83, 0x1000, s83
	s_cselect_b32 s77, 0x3000, s77
	s_cmp_eq_u32 s64, 1
	s_cselect_b32 s83, 0x1e00, s83
	s_cselect_b32 s77, 0x3e00, s77
	s_cmp_eq_u32 s64, 2
	s_cselect_b32 s83, 0x2d00, s83
	s_cselect_b32 s77, 0x4d00, s77
	s_cmp_eq_u32 s64, 3
	s_cselect_b32 s83, 0x0, s83
	s_cselect_b32 s77, 0x3c00, s77
	s_cmp_eq_u32 s64, 4
	s_cselect_b32 s83, 0x0, s83
	s_cselect_b32 s77, 0x4b00, s77
	s_sub_i32 s4, s5, s4
	v_add_u32_e32 v240, s4, v236
	ds_read2_b32 v[204:205], v240 offset0:192 offset1:193
	ds_read2_b32 v[206:207], v240 offset0:194 offset1:195
	ds_read2_b32 v[208:209], v240 offset0:196 offset1:197
	ds_read2_b32 v[210:211], v240 offset0:198 offset1:199
	ds_read2_b32 v[80:81], v240 offset0:128 offset1:129
	ds_read2_b32 v[82:83], v240 offset0:130 offset1:131
	ds_read2_b32 v[84:85], v240 offset0:132 offset1:133
	ds_read2_b32 v[86:87], v240 offset0:134 offset1:135
	ds_read2_b32 v[180:181], v240 offset0:64 offset1:65
	ds_read2_b32 v[182:183], v240 offset0:66 offset1:67
	ds_read2_b32 v[184:185], v240 offset0:68 offset1:69
	ds_read2_b32 v[186:187], v240 offset0:70 offset1:71
	ds_read2_b32 v[212:213], v240 offset0:0 offset1:1
	ds_read2_b32 v[214:215], v240 offset0:2 offset1:3
	ds_read2_b32 v[242:243], v240 offset0:4 offset1:5
	ds_read2_b32 v[244:245], v240 offset0:6 offset1:7
	v_xor_b32_e32 v76, 0x80000000, v239
	v_xor_b32_e32 v77, 0x80000000, v239
	v_xor_b32_e32 v78, 0x80000000, v239
	v_xor_b32_e32 v79, 0x80000000, v239
	v_mov_b32_e32 v96, 0
	v_mov_b32_e32 v97, 0
	v_mov_b32_e32 v98, 0
	v_mov_b32_e32 v99, 0
	v_mov_b32_e32 v88, 0
	v_mov_b32_e32 v89, 0
	v_mov_b32_e32 v90, 0
	v_mov_b32_e32 v91, 0
	v_mov_b32_e32 v72, 0
	v_mov_b32_e32 v73, 0
	v_mov_b32_e32 v74, 0
	v_mov_b32_e32 v75, 0
	v_mov_b32_e32 v68, 0
	v_mov_b32_e32 v69, 0
	v_mov_b32_e32 v70, 0
	v_mov_b32_e32 v71, 0
	v_mov_b32_e32 v222, 0
	v_mov_b32_e32 v64, 0
	v_mov_b32_e32 v65, 0
	v_mov_b32_e32 v66, 0
	v_mov_b32_e32 v67, 0
	v_mov_b32_e32 v60, 0
	v_mov_b32_e32 v61, 0
	v_mov_b32_e32 v62, 0
	v_mov_b32_e32 v63, 0
	v_mov_b32_e32 v56, 0
	v_mov_b32_e32 v57, 0
	v_mov_b32_e32 v58, 0
	v_mov_b32_e32 v59, 0
	v_mov_b32_e32 v52, 0
	v_mov_b32_e32 v53, 0
	v_mov_b32_e32 v54, 0
	v_mov_b32_e32 v55, 0
	v_mov_b32_e32 v223, 0
	v_mov_b32_e32 v128, 0
	v_mov_b32_e32 v129, 0
	v_mov_b32_e32 v130, 0
	v_mov_b32_e32 v131, 0
	v_mov_b32_e32 v124, 0
	v_mov_b32_e32 v125, 0
	v_mov_b32_e32 v126, 0
	v_mov_b32_e32 v127, 0
	v_mov_b32_e32 v120, 0
	v_mov_b32_e32 v121, 0
	v_mov_b32_e32 v122, 0
	v_mov_b32_e32 v123, 0
	v_mov_b32_e32 v116, 0
	v_mov_b32_e32 v117, 0
	v_mov_b32_e32 v118, 0
	v_mov_b32_e32 v119, 0
	v_mov_b32_e32 v224, 0
	v_mov_b32_e32 v112, 0
	v_mov_b32_e32 v113, 0
	v_mov_b32_e32 v114, 0
	v_mov_b32_e32 v115, 0
	v_mov_b32_e32 v108, 0
	v_mov_b32_e32 v109, 0
	v_mov_b32_e32 v110, 0
	v_mov_b32_e32 v111, 0
	v_mov_b32_e32 v104, 0
	v_mov_b32_e32 v105, 0
	v_mov_b32_e32 v106, 0
	v_mov_b32_e32 v107, 0
	v_mov_b32_e32 v100, 0
	v_mov_b32_e32 v101, 0
	v_mov_b32_e32 v102, 0
	v_mov_b32_e32 v103, 0
	v_mov_b32_e32 v225, 0
	s_waitcnt lgkmcnt(0)
	v_sub_f32_e32 v204, v204, v239
	v_sub_f32_e32 v205, v205, v239
	v_sub_f32_e32 v206, v206, v239
	v_sub_f32_e32 v207, v207, v239
	v_sub_f32_e32 v208, v208, v239
	v_sub_f32_e32 v209, v209, v239
	v_sub_f32_e32 v210, v210, v239
	v_sub_f32_e32 v211, v211, v239
	v_cndmask_b32_e64 v204, v238, v204, s[0:1]
	v_cndmask_b32_e64 v205, v238, v205, s[6:7]
	v_cndmask_b32_e64 v206, v238, v206, s[8:9]
	v_cndmask_b32_e64 v207, v238, v207, s[10:11]
	v_cndmask_b32_e64 v208, v238, v208, s[12:13]
	v_cndmask_b32_e64 v209, v238, v209, s[14:15]
	v_cndmask_b32_e64 v210, v238, v210, s[16:17]
	v_cndmask_b32_e64 v211, v238, v211, s[18:19]
	v_sub_f32_e32 v80, v80, v239
	v_sub_f32_e32 v81, v81, v239
	v_sub_f32_e32 v82, v82, v239
	v_sub_f32_e32 v83, v83, v239
	v_sub_f32_e32 v84, v84, v239
	v_sub_f32_e32 v85, v85, v239
	v_sub_f32_e32 v86, v86, v239
	v_sub_f32_e32 v87, v87, v239
	v_cndmask_b32_e64 v80, v238, v80, s[0:1]
	v_cndmask_b32_e64 v81, v238, v81, s[6:7]
	v_cndmask_b32_e64 v82, v238, v82, s[8:9]
	v_cndmask_b32_e64 v83, v238, v83, s[10:11]
	v_cndmask_b32_e64 v84, v238, v84, s[12:13]
	v_cndmask_b32_e64 v85, v238, v85, s[14:15]
	v_cndmask_b32_e64 v86, v238, v86, s[16:17]
	v_cndmask_b32_e64 v87, v238, v87, s[18:19]
	v_sub_f32_e32 v180, v180, v239
	v_sub_f32_e32 v181, v181, v239
	v_sub_f32_e32 v182, v182, v239
	v_sub_f32_e32 v183, v183, v239
	v_sub_f32_e32 v184, v184, v239
	v_sub_f32_e32 v185, v185, v239
	v_sub_f32_e32 v186, v186, v239
	v_sub_f32_e32 v187, v187, v239
	v_cndmask_b32_e64 v180, v238, v180, s[0:1]
	v_cndmask_b32_e64 v181, v238, v181, s[6:7]
	v_cndmask_b32_e64 v182, v238, v182, s[8:9]
	v_cndmask_b32_e64 v183, v238, v183, s[10:11]
	v_cndmask_b32_e64 v184, v238, v184, s[12:13]
	v_cndmask_b32_e64 v185, v238, v185, s[14:15]
	v_cndmask_b32_e64 v186, v238, v186, s[16:17]
	v_cndmask_b32_e64 v187, v238, v187, s[18:19]
	v_sub_f32_e32 v212, v212, v239
	v_sub_f32_e32 v213, v213, v239
	v_sub_f32_e32 v214, v214, v239
	v_sub_f32_e32 v215, v215, v239
	v_sub_f32_e32 v242, v242, v239
	v_sub_f32_e32 v243, v243, v239
	v_sub_f32_e32 v244, v244, v239
	v_sub_f32_e32 v245, v245, v239
	v_cndmask_b32_e64 v212, v238, v212, s[0:1]
	v_cndmask_b32_e64 v213, v238, v213, s[6:7]
	v_cndmask_b32_e64 v214, v238, v214, s[8:9]
	v_cndmask_b32_e64 v215, v238, v215, s[10:11]
	v_cndmask_b32_e64 v242, v238, v242, s[12:13]
	v_cndmask_b32_e64 v243, v238, v243, s[14:15]
	v_cndmask_b32_e64 v244, v238, v244, s[16:17]
	v_cndmask_b32_e64 v245, v238, v245, s[18:19]
	v_add_u32_e32 v240, 0x400, v240
	s_mov_b32 s92, -1
	s_mov_b32 s63, 2
	s_mov_b32 s63, 3
	s_add_u32 s92, s92, 1
	s_add_u32 s63, s63, 1
	s_and_b32 s63, s63, 3
	s_sub_i32 s80, s92, s60
	s_sub_i32 s89, s92, s76
	s_cmp_lt_i32 s80, 0
	s_cselect_b32 s89, s92, s89
	s_max_i32 s89, s89, 0
	s_min_i32 s89, s89, 7
	s_lshr_b32 s81, s89, 1
	s_lshl_b32 s81, s81, 14
	s_add_u32 s81, s81, 0x8000
	s_and_b32 s82, s89, 1
	s_lshl_b32 s20, s82, 8
	s_add_u32 s23, s81, s20
	s_lshl_b32 s20, s82, 10
	s_add_u32 s33, s81, s20
	s_add_u32 s33, s33, 0x2000
	s_cmp_ge_i32 s80, 0
	s_cselect_b32 s20, 1, 0
	s_cmp_lt_i32 s80, s76
	s_cselect_b32 s20, s20, 0
	s_cmp_lg_u32 s20, 0
	s_cbranch_scc0 .Latt_cs2
	s_lshl_b32 s81, s63, 14
	s_add_u32 s81, s81, 0x18000
	s_lshr_b32 s20, s63, 1
	s_lshl_b32 s20, s20, 4
	s_add_u32 s81, s81, s20
	s_add_u32 s82, s81, 0x2000
	s_cmp_eq_u32 s63, 3
	s_cselect_b32 s81, s83, s81
	s_cselect_b32 s82, s77, s82
	s_add_u32 s23, s81, s97
	s_add_u32 s33, s82, s90

.Latt_went:
	s_mov_b32 s85, 0
	s_cmp_eq_u32 s76, 8
	s_cbranch_scc1 .Latt_n8
	s_add_u32 s92, s92, 1
	s_add_u32 s63, s63, 1
	s_and_b32 s63, s63, 3
	s_sub_i32 s80, s92, s60
	s_sub_i32 s89, s92, s76
	s_cmp_lt_i32 s80, 0
	s_cselect_b32 s89, s92, s89
	s_max_i32 s89, s89, 0
	s_min_i32 s89, s89, 7
	s_lshr_b32 s81, s89, 1
	s_lshl_b32 s81, s81, 14
	s_add_u32 s81, s81, 0x8000
	s_and_b32 s82, s89, 1
	s_lshl_b32 s20, s82, 8
	s_add_u32 s23, s81, s20
	s_lshl_b32 s20, s82, 10
	s_add_u32 s33, s81, s20
	s_add_u32 s33, s33, 0x2000
	s_cmp_ge_i32 s80, 0
	s_cselect_b32 s20, 1, 0
	s_cmp_lt_i32 s80, s76
	s_cselect_b32 s20, s20, 0
	s_cmp_lg_u32 s20, 0
	s_cbranch_scc0 .Latt_cs4
	s_lshl_b32 s81, s63, 14
	s_add_u32 s81, s81, 0x18000
	s_lshr_b32 s20, s63, 1
	s_lshl_b32 s20, s20, 4
	s_add_u32 s81, s81, s20
	s_add_u32 s82, s81, 0x2000
	s_cmp_eq_u32 s63, 3
	s_cselect_b32 s81, s83, s81
	s_cselect_b32 s82, s77, s82
	s_add_u32 s23, s81, s97
	s_add_u32 s33, s82, s90
.Latt_cs4:
	s_add_u32 s21, s92, 2
	s_cmp_lt_u32 s21, s88
	s_cselect_b32 s89, 1, 0
	s_add_u32 s20, s21, 1
	s_cmp_lt_u32 s20, s88
	s_cselect_b32 s82, 1, 0
	s_add_u32 s21, s21, s93
	s_lshl_b32 s22, s21, 7
	s_add_u32 s22, s22, s62
	s_lshl_b32 s21, s21, 16
	s_add_u32 s21, s21, s61
	s_add_u32 s20, s63, 2
	s_and_b32 s20, s20, 3
	s_lshl_b32 s84, s20, 14
	s_add_u32 s84, s84, 0x18000
	s_lshr_b32 s80, s20, 1
	s_lshl_b32 s80, s80, 4
	s_add_u32 s84, s84, s80
	s_add_u32 s87, s84, 0x2000
	s_cmp_eq_u32 s20, 3
	s_cselect_b32 s84, s83, s84
	s_cselect_b32 s87, s77, s87
	s_add_u32 s84, s84, s94
	s_add_u32 s87, s87, s94
	s_add_u32 s20, s63, 3
	s_and_b32 s20, s20, 3
	s_lshl_b32 s80, s20, 14
	s_add_u32 s80, s80, 0x18000
	s_lshr_b32 s95, s20, 1
	s_lshl_b32 s95, s95, 4
	s_add_u32 s80, s80, s95
	s_add_u32 s81, s80, 0x2000
	s_cmp_eq_u32 s20, 3
	s_cselect_b32 s80, s83, s80
	s_cselect_b32 s81, s77, s81
	s_add_u32 s80, s80, s94
	s_add_u32 s81, s81, s94
	s_waitcnt lgkmcnt(0)
	s_waitcnt vmcnt(0)
	s_cmp_lt_u32 s92, s88
	s_cbranch_scc0 .Latt_sb3
	s_barrier
.Latt_sb3:
	s_cmp_lg_u32 s89, 0
	s_cbranch_scc0 .Latt_sk3
	s_mov_b32 m0, s84
	s_nop 0
	buffer_load_dwordx4 v241, s[24:27], s21 offen lds
	s_mov_b32 m0, s87
	s_nop 0
	buffer_load_dwordx4 v255, s[40:43], s22 offen lds
	s_cmp_lg_u32 s82, 0
	s_cbranch_scc0 .Latt_sk3
	s_add_u32 s21, s21, 0x10000
	s_add_u32 s22, s22, 0x80
	s_mov_b32 m0, s80
	s_nop 0
	buffer_load_dwordx4 v241, s[24:27], s21 offen lds
	s_mov_b32 m0, s81
	s_nop 0
	buffer_load_dwordx4 v255, s[40:43], s22 offen lds
.Latt_sk3:
	v_add_u32_e32 v251, s23, v233
	v_add_u32_e32 v253, s33, v234
	ds_read_b128 v[48:51], v251 offset:0
	ds_read_b128 v[40:43], v251 offset:4096
	ds_read_b128 v[44:47], v251 offset:2048
	ds_read_b128 v[36:39], v251 offset:6144
	ds_read_b128 v[16:19], v253 offset:0
	ds_read_b128 v[12:15], v253 offset:2048
	ds_read_b128 v[8:11], v253 offset:4096
	ds_read_b128 v[4:7], v253 offset:6144
	ds_read2_b32 v[212:213], v240 offset0:0 offset1:1
	ds_read2_b32 v[214:215], v240 offset0:2 offset1:3
	ds_read2_b32 v[242:243], v240 offset0:4 offset1:5
	ds_read2_b32 v[244:245], v240 offset0:6 offset1:7
	v_mfma_f32_16x16x32_bf16 v[188:191], v[176:179], v[132:135], v[204:207]
	v_mfma_f32_16x16x32_bf16 v[192:195], v[168:171], v[132:135], v[208:211]
	v_mfma_f32_16x16x32_bf16 v[188:191], v[172:175], v[136:139], v[188:191]
	v_mfma_f32_16x16x32_bf16 v[192:195], v[164:167], v[136:139], v[192:195]
	s_nop 6
	v_exp_f32_e32 v188, v188
	v_exp_f32_e32 v189, v189
	v_exp_f32_e32 v190, v190
	v_exp_f32_e32 v191, v191
	v_exp_f32_e32 v192, v192
	v_exp_f32_e32 v193, v193
	v_exp_f32_e32 v194, v194
	v_exp_f32_e32 v195, v195
	v_cvt_pk_bf16_f32 v246, v188, v189
	v_cvt_pk_bf16_f32 v247, v190, v191
	v_cvt_pk_bf16_f32 v248, v192, v193
	v_cvt_pk_bf16_f32 v249, v194, v195
	v_add_f32_e32 v188, v188, v189
	v_add_f32_e32 v190, v190, v191
	v_add_f32_e32 v192, v192, v193
	v_add_f32_e32 v194, v194, v195
	v_add_f32_e32 v188, v188, v190
	v_add_f32_e32 v192, v192, v194
	v_add_f32_e32 v188, v188, v192
	v_add_f32_e32 v222, v222, v188
	s_waitcnt lgkmcnt(0)
	v_sub_f32_e32 v212, v212, v239
	v_sub_f32_e32 v213, v213, v239
	v_sub_f32_e32 v214, v214, v239
	v_mfma_f32_16x16x32_bf16 v[96:99], v[32:35], v[246:249], v[96:99]
	v_sub_f32_e32 v215, v215, v239
	v_sub_f32_e32 v242, v242, v239
	v_sub_f32_e32 v243, v243, v239
	v_mfma_f32_16x16x32_bf16 v[88:91], v[28:31], v[246:249], v[88:91]
	v_sub_f32_e32 v244, v244, v239
	v_sub_f32_e32 v245, v245, v239
	v_cndmask_b32_e64 v212, v238, v212, s[0:1]
	v_mfma_f32_16x16x32_bf16 v[72:75], v[24:27], v[246:249], v[72:75]
	v_cndmask_b32_e64 v213, v238, v213, s[6:7]
	v_cndmask_b32_e64 v214, v238, v214, s[8:9]
	v_cndmask_b32_e64 v215, v238, v215, s[10:11]
	v_mfma_f32_16x16x32_bf16 v[68:71], v[20:23], v[246:249], v[68:71]
	v_cndmask_b32_e64 v242, v238, v242, s[12:13]
	v_cndmask_b32_e64 v243, v238, v243, s[14:15]
	v_cndmask_b32_e64 v244, v238, v244, s[16:17]
	v_cndmask_b32_e64 v245, v238, v245, s[18:19]
	v_add_u32_e32 v240, 0x100, v240
	s_add_u32 s92, s92, 1
	s_add_u32 s63, s63, 1
	s_and_b32 s63, s63, 3
	s_sub_i32 s80, s92, s60
	s_sub_i32 s89, s92, s76
	s_cmp_lt_i32 s80, 0
	s_cselect_b32 s89, s92, s89
	s_max_i32 s89, s89, 0
	s_min_i32 s89, s89, 7
	s_lshr_b32 s81, s89, 1
	s_lshl_b32 s81, s81, 14
	s_add_u32 s81, s81, 0x8000
	s_and_b32 s82, s89, 1
	s_lshl_b32 s20, s82, 8
	s_add_u32 s23, s81, s20
	s_lshl_b32 s20, s82, 10
	s_add_u32 s33, s81, s20
	s_add_u32 s33, s33, 0x2000
	s_cmp_ge_i32 s80, 0
	s_cselect_b32 s20, 1, 0
	s_cmp_lt_i32 s80, s76
	s_cselect_b32 s20, s20, 0
	s_cmp_lg_u32 s20, 0
	s_cbranch_scc0 .Latt_cs6
	s_lshl_b32 s81, s63, 14
	s_add_u32 s81, s81, 0x18000
	s_lshr_b32 s20, s63, 1
	s_lshl_b32 s20, s20, 4
	s_add_u32 s81, s81, s20
	s_add_u32 s82, s81, 0x2000
	s_cmp_eq_u32 s63, 3
	s_cselect_b32 s81, s83, s81
	s_cselect_b32 s82, s77, s82
	s_add_u32 s23, s81, s97
	s_add_u32 s33, s82, s90
.Latt_cs6:
	s_waitcnt lgkmcnt(0)
	v_add_u32_e32 v251, s23, v233
	v_add_u32_e32 v253, s33, v234
	ds_read_b128 v[176:179], v251 offset:0
	ds_read_b128 v[168:171], v251 offset:4096
	ds_read_b128 v[172:175], v251 offset:2048
	ds_read_b128 v[164:167], v251 offset:6144
	ds_read_b128 v[32:35], v253 offset:0
	ds_read_b128 v[28:31], v253 offset:2048
	ds_read_b128 v[24:27], v253 offset:4096
	ds_read_b128 v[20:23], v253 offset:6144
	ds_read2_b32 v[180:181], v240 offset0:0 offset1:1
	ds_read2_b32 v[182:183], v240 offset0:2 offset1:3
	ds_read2_b32 v[184:185], v240 offset0:4 offset1:5
	ds_read2_b32 v[186:187], v240 offset0:6 offset1:7
	v_mfma_f32_16x16x32_bf16 v[188:191], v[48:51], v[140:143], v[204:207]
	v_mfma_f32_16x16x32_bf16 v[192:195], v[40:43], v[140:143], v[208:211]
	v_mfma_f32_16x16x32_bf16 v[188:191], v[44:47], v[144:147], v[188:191]
	v_mfma_f32_16x16x32_bf16 v[192:195], v[36:39], v[144:147], v[192:195]
	v_mfma_f32_16x16x32_bf16 v[196:199], v[48:51], v[132:135], v[212:215]
	v_mfma_f32_16x16x32_bf16 v[200:203], v[40:43], v[132:135], v[242:245]
	v_mfma_f32_16x16x32_bf16 v[196:199], v[44:47], v[136:139], v[196:199]
	v_mfma_f32_16x16x32_bf16 v[200:203], v[36:39], v[136:139], v[200:203]
	s_nop 2
	v_exp_f32_e32 v188, v188
	v_exp_f32_e32 v189, v189
	v_exp_f32_e32 v190, v190
	v_exp_f32_e32 v191, v191
	v_exp_f32_e32 v192, v192
	v_exp_f32_e32 v193, v193
	v_exp_f32_e32 v194, v194
	v_exp_f32_e32 v195, v195
	v_cvt_pk_bf16_f32 v246, v188, v189
	v_cvt_pk_bf16_f32 v247, v190, v191
	v_cvt_pk_bf16_f32 v248, v192, v193
	v_cvt_pk_bf16_f32 v249, v194, v195
	v_add_f32_e32 v188, v188, v189
	v_add_f32_e32 v190, v190, v191
	v_add_f32_e32 v192, v192, v193
	v_add_f32_e32 v194, v194, v195
	v_add_f32_e32 v188, v188, v190
	v_add_f32_e32 v192, v192, v194
	v_add_f32_e32 v188, v188, v192
	v_add_f32_e32 v223, v223, v188
	v_exp_f32_e32 v196, v196
	v_exp_f32_e32 v197, v197
	v_exp_f32_e32 v198, v198
	v_exp_f32_e32 v199, v199
	v_mfma_f32_16x16x32_bf16 v[64:67], v[16:19], v[246:249], v[64:67]
	v_exp_f32_e32 v200, v200
	v_exp_f32_e32 v201, v201
	v_exp_f32_e32 v202, v202
	v_exp_f32_e32 v203, v203
	v_mfma_f32_16x16x32_bf16 v[60:63], v[12:15], v[246:249], v[60:63]
	v_cvt_pk_bf16_f32 v92, v196, v197
	v_cvt_pk_bf16_f32 v93, v198, v199
	v_cvt_pk_bf16_f32 v94, v200, v201
	v_cvt_pk_bf16_f32 v95, v202, v203
	v_mfma_f32_16x16x32_bf16 v[56:59], v[8:11], v[246:249], v[56:59]
	v_add_f32_e32 v196, v196, v197
	v_add_f32_e32 v198, v198, v199
	v_add_f32_e32 v200, v200, v201
	v_add_f32_e32 v202, v202, v203
	v_mfma_f32_16x16x32_bf16 v[52:55], v[4:7], v[246:249], v[52:55]
	v_add_f32_e32 v196, v196, v198
	v_add_f32_e32 v200, v200, v202
	v_add_f32_e32 v196, v196, v200
	v_add_f32_e32 v222, v222, v196
	s_waitcnt lgkmcnt(0)
	v_sub_f32_e32 v180, v180, v239
	v_sub_f32_e32 v181, v181, v239
	v_sub_f32_e32 v182, v182, v239
	v_mfma_f32_16x16x32_bf16 v[96:99], v[16:19], v[92:95], v[96:99]
	v_sub_f32_e32 v183, v183, v239
	v_sub_f32_e32 v184, v184, v239
	v_sub_f32_e32 v185, v185, v239
	v_mfma_f32_16x16x32_bf16 v[88:91], v[12:15], v[92:95], v[88:91]
	v_sub_f32_e32 v186, v186, v239
	v_sub_f32_e32 v187, v187, v239
	v_cndmask_b32_e64 v180, v238, v180, s[0:1]
	v_mfma_f32_16x16x32_bf16 v[72:75], v[8:11], v[92:95], v[72:75]
	v_cndmask_b32_e64 v181, v238, v181, s[6:7]
	v_cndmask_b32_e64 v182, v238, v182, s[8:9]
	v_cndmask_b32_e64 v183, v238, v183, s[10:11]
	v_mfma_f32_16x16x32_bf16 v[68:71], v[4:7], v[92:95], v[68:71]
	v_cndmask_b32_e64 v184, v238, v184, s[12:13]
	v_cndmask_b32_e64 v185, v238, v185, s[14:15]
	v_cndmask_b32_e64 v186, v238, v186, s[16:17]
	v_cndmask_b32_e64 v187, v238, v187, s[18:19]
	v_add_u32_e32 v240, 0x100, v240
	s_add_u32 s92, s92, 1
	s_add_u32 s63, s63, 1
	s_and_b32 s63, s63, 3
	s_sub_i32 s80, s92, s60
	s_sub_i32 s89, s92, s76
	s_cmp_lt_i32 s80, 0
	s_cselect_b32 s89, s92, s89
	s_max_i32 s89, s89, 0
	s_min_i32 s89, s89, 7
	s_lshr_b32 s81, s89, 1
	s_lshl_b32 s81, s81, 14
	s_add_u32 s81, s81, 0x8000
	s_and_b32 s82, s89, 1
	s_lshl_b32 s20, s82, 8
	s_add_u32 s23, s81, s20
	s_lshl_b32 s20, s82, 10
	s_add_u32 s33, s81, s20
	s_add_u32 s33, s33, 0x2000
	s_cmp_ge_i32 s80, 0
	s_cselect_b32 s20, 1, 0
	s_cmp_lt_i32 s80, s76
	s_cselect_b32 s20, s20, 0
	s_cmp_lg_u32 s20, 0
	s_cbranch_scc0 .Latt_cs8
	s_lshl_b32 s81, s63, 14
	s_add_u32 s81, s81, 0x18000
	s_lshr_b32 s20, s63, 1
	s_lshl_b32 s20, s20, 4
	s_add_u32 s81, s81, s20
	s_add_u32 s82, s81, 0x2000
	s_cmp_eq_u32 s63, 3
	s_cselect_b32 s81, s83, s81
	s_cselect_b32 s82, s77, s82
	s_add_u32 s23, s81, s97
	s_add_u32 s33, s82, s90

.Latt_sk7:
	v_add_u32_e32 v251, s23, v233
	v_add_u32_e32 v253, s33, v234
	ds_read_b128 v[48:51], v251 offset:0
	ds_read_b128 v[40:43], v251 offset:4096
	ds_read_b128 v[44:47], v251 offset:2048
	ds_read_b128 v[36:39], v251 offset:6144
	ds_read_b128 v[16:19], v253 offset:0
	ds_read_b128 v[12:15], v253 offset:2048
	ds_read_b128 v[8:11], v253 offset:4096
	ds_read_b128 v[4:7], v253 offset:6144
	ds_read2_b32 v[80:81], v240 offset0:0 offset1:1
	ds_read2_b32 v[82:83], v240 offset0:2 offset1:3
	ds_read2_b32 v[84:85], v240 offset0:4 offset1:5
	ds_read2_b32 v[86:87], v240 offset0:6 offset1:7
	v_mfma_f32_16x16x32_bf16 v[188:191], v[176:179], v[148:151], v[204:207]
	v_mfma_f32_16x16x32_bf16 v[192:195], v[168:171], v[148:151], v[208:211]
	v_mfma_f32_16x16x32_bf16 v[188:191], v[172:175], v[152:155], v[188:191]
	v_mfma_f32_16x16x32_bf16 v[192:195], v[164:167], v[152:155], v[192:195]
	v_mfma_f32_16x16x32_bf16 v[196:199], v[176:179], v[140:143], v[212:215]
	v_mfma_f32_16x16x32_bf16 v[200:203], v[168:171], v[140:143], v[242:245]
	v_mfma_f32_16x16x32_bf16 v[196:199], v[172:175], v[144:147], v[196:199]
	v_mfma_f32_16x16x32_bf16 v[200:203], v[164:167], v[144:147], v[200:203]
	s_nop 2
	v_exp_f32_e32 v188, v188
	v_exp_f32_e32 v189, v189
	v_exp_f32_e32 v190, v190
	v_exp_f32_e32 v191, v191
	v_exp_f32_e32 v192, v192
	v_exp_f32_e32 v193, v193
	v_exp_f32_e32 v194, v194
	v_exp_f32_e32 v195, v195
	v_cvt_pk_bf16_f32 v246, v188, v189
	v_cvt_pk_bf16_f32 v247, v190, v191
	v_cvt_pk_bf16_f32 v248, v192, v193
	v_cvt_pk_bf16_f32 v249, v194, v195
	v_add_f32_e32 v188, v188, v189
	v_add_f32_e32 v190, v190, v191
	v_add_f32_e32 v192, v192, v193
	v_add_f32_e32 v194, v194, v195
	v_add_f32_e32 v188, v188, v190
	v_add_f32_e32 v192, v192, v194
	v_add_f32_e32 v188, v188, v192
	v_add_f32_e32 v224, v224, v188
	v_mfma_f32_16x16x32_bf16 v[188:191], v[176:179], v[132:135], v[180:183]
	v_mfma_f32_16x16x32_bf16 v[192:195], v[168:171], v[132:135], v[184:187]
	v_mfma_f32_16x16x32_bf16 v[188:191], v[172:175], v[136:139], v[188:191]
	v_mfma_f32_16x16x32_bf16 v[192:195], v[164:167], v[136:139], v[192:195]
	v_exp_f32_e32 v196, v196
	v_exp_f32_e32 v197, v197
	v_exp_f32_e32 v198, v198
	v_exp_f32_e32 v199, v199
	v_mfma_f32_16x16x32_bf16 v[128:131], v[32:35], v[246:249], v[128:131]
	v_exp_f32_e32 v200, v200
	v_exp_f32_e32 v201, v201
	v_exp_f32_e32 v202, v202
	v_exp_f32_e32 v203, v203
	v_mfma_f32_16x16x32_bf16 v[124:127], v[28:31], v[246:249], v[124:127]
	v_cvt_pk_bf16_f32 v92, v196, v197
	v_cvt_pk_bf16_f32 v93, v198, v199
	v_cvt_pk_bf16_f32 v94, v200, v201
	v_cvt_pk_bf16_f32 v95, v202, v203
	v_mfma_f32_16x16x32_bf16 v[120:123], v[24:27], v[246:249], v[120:123]
	v_add_f32_e32 v196, v196, v197
	v_add_f32_e32 v198, v198, v199
	v_add_f32_e32 v200, v200, v201
	v_add_f32_e32 v202, v202, v203
	v_mfma_f32_16x16x32_bf16 v[116:119], v[20:23], v[246:249], v[116:119]
	v_add_f32_e32 v196, v196, v198
	v_add_f32_e32 v200, v200, v202
	v_add_f32_e32 v196, v196, v200
	v_add_f32_e32 v223, v223, v196
	v_exp_f32_e32 v188, v188
	v_exp_f32_e32 v189, v189
	v_exp_f32_e32 v190, v190
	v_exp_f32_e32 v191, v191
	v_mfma_f32_16x16x32_bf16 v[64:67], v[32:35], v[92:95], v[64:67]
	v_exp_f32_e32 v192, v192
	v_exp_f32_e32 v193, v193
	v_exp_f32_e32 v194, v194
	v_exp_f32_e32 v195, v195
	v_mfma_f32_16x16x32_bf16 v[60:63], v[28:31], v[92:95], v[60:63]
	v_cvt_pk_bf16_f32 v246, v188, v189
	v_cvt_pk_bf16_f32 v247, v190, v191
	v_cvt_pk_bf16_f32 v248, v192, v193
	v_cvt_pk_bf16_f32 v249, v194, v195
	v_mfma_f32_16x16x32_bf16 v[56:59], v[24:27], v[92:95], v[56:59]
	v_add_f32_e32 v188, v188, v189
	v_add_f32_e32 v190, v190, v191
	v_add_f32_e32 v192, v192, v193
	v_add_f32_e32 v194, v194, v195
	v_mfma_f32_16x16x32_bf16 v[52:55], v[20:23], v[92:95], v[52:55]
	v_add_f32_e32 v188, v188, v190
	v_add_f32_e32 v192, v192, v194
	v_add_f32_e32 v188, v188, v192
	v_add_f32_e32 v222, v222, v188
	s_waitcnt lgkmcnt(0)
	v_sub_f32_e32 v80, v80, v239
	v_sub_f32_e32 v81, v81, v239
	v_sub_f32_e32 v82, v82, v239
	v_mfma_f32_16x16x32_bf16 v[96:99], v[32:35], v[246:249], v[96:99]
	v_sub_f32_e32 v83, v83, v239
	v_sub_f32_e32 v84, v84, v239
	v_sub_f32_e32 v85, v85, v239
	v_mfma_f32_16x16x32_bf16 v[88:91], v[28:31], v[246:249], v[88:91]
	v_sub_f32_e32 v86, v86, v239
	v_sub_f32_e32 v87, v87, v239
	v_cndmask_b32_e64 v80, v238, v80, s[0:1]
	v_mfma_f32_16x16x32_bf16 v[72:75], v[24:27], v[246:249], v[72:75]
	v_cndmask_b32_e64 v81, v238, v81, s[6:7]
	v_cndmask_b32_e64 v82, v238, v82, s[8:9]
	v_cndmask_b32_e64 v83, v238, v83, s[10:11]
	v_mfma_f32_16x16x32_bf16 v[68:71], v[20:23], v[246:249], v[68:71]
	v_cndmask_b32_e64 v84, v238, v84, s[12:13]
	v_cndmask_b32_e64 v85, v238, v85, s[14:15]
	v_cndmask_b32_e64 v86, v238, v86, s[16:17]
	v_cndmask_b32_e64 v87, v238, v87, s[18:19]
	v_add_u32_e32 v240, 0x100, v240
	s_add_u32 s92, s92, 1
	s_add_u32 s63, s63, 1
	s_and_b32 s63, s63, 3
	s_sub_i32 s80, s92, s60
	s_sub_i32 s89, s92, s76
	s_cmp_lt_i32 s80, 0
	s_cselect_b32 s89, s92, s89
	s_max_i32 s89, s89, 0
	s_min_i32 s89, s89, 7
	s_lshr_b32 s81, s89, 1
	s_lshl_b32 s81, s81, 14
	s_add_u32 s81, s81, 0x8000
	s_and_b32 s82, s89, 1
	s_lshl_b32 s20, s82, 8
	s_add_u32 s23, s81, s20
	s_lshl_b32 s20, s82, 10
	s_add_u32 s33, s81, s20
	s_add_u32 s33, s33, 0x2000
	s_cmp_ge_i32 s80, 0
	s_cselect_b32 s20, 1, 0
	s_cmp_lt_i32 s80, s76
	s_cselect_b32 s20, s20, 0
	s_cmp_lg_u32 s20, 0
	s_cbranch_scc0 .Latt_cs10
	s_lshl_b32 s81, s63, 14
	s_add_u32 s81, s81, 0x18000
	s_lshr_b32 s20, s63, 1
	s_lshl_b32 s20, s20, 4
	s_add_u32 s81, s81, s20
	s_add_u32 s82, s81, 0x2000
	s_cmp_eq_u32 s63, 3
	s_cselect_b32 s81, s83, s81
	s_cselect_b32 s82, s77, s82
	s_add_u32 s23, s81, s97
	s_add_u32 s33, s82, s90
.Latt_cs10:
	s_waitcnt lgkmcnt(0)
	v_add_u32_e32 v251, s23, v233
	v_add_u32_e32 v253, s33, v234
	ds_read_b128 v[176:179], v251 offset:0
	ds_read_b128 v[168:171], v251 offset:4096
	ds_read_b128 v[172:175], v251 offset:2048
	ds_read_b128 v[164:167], v251 offset:6144
	ds_read_b128 v[32:35], v253 offset:0
	ds_read_b128 v[28:31], v253 offset:2048
	ds_read_b128 v[24:27], v253 offset:4096
	ds_read_b128 v[20:23], v253 offset:6144
	v_mfma_f32_16x16x32_bf16 v[188:191], v[48:51], v[156:159], v[204:207]
	v_mfma_f32_16x16x32_bf16 v[192:195], v[40:43], v[156:159], v[208:211]
	v_mfma_f32_16x16x32_bf16 v[188:191], v[44:47], v[160:163], v[188:191]
	v_mfma_f32_16x16x32_bf16 v[192:195], v[36:39], v[160:163], v[192:195]
	ds_read2_b32 v[204:205], v240 offset0:0 offset1:1
	ds_read2_b32 v[206:207], v240 offset0:2 offset1:3
	ds_read2_b32 v[208:209], v240 offset0:4 offset1:5
	ds_read2_b32 v[210:211], v240 offset0:6 offset1:7
	v_mfma_f32_16x16x32_bf16 v[196:199], v[48:51], v[148:151], v[212:215]
	v_mfma_f32_16x16x32_bf16 v[200:203], v[40:43], v[148:151], v[242:245]
	v_mfma_f32_16x16x32_bf16 v[196:199], v[44:47], v[152:155], v[196:199]
	v_mfma_f32_16x16x32_bf16 v[200:203], v[36:39], v[152:155], v[200:203]
	v_exp_f32_e32 v188, v188
	v_exp_f32_e32 v189, v189
	v_exp_f32_e32 v190, v190
	v_exp_f32_e32 v191, v191
	v_exp_f32_e32 v192, v192
	v_exp_f32_e32 v193, v193
	v_exp_f32_e32 v194, v194
	v_exp_f32_e32 v195, v195
	v_cvt_pk_bf16_f32 v246, v188, v189
	v_cvt_pk_bf16_f32 v247, v190, v191
	v_cvt_pk_bf16_f32 v248, v192, v193
	v_cvt_pk_bf16_f32 v249, v194, v195
	v_add_f32_e32 v188, v188, v189
	v_add_f32_e32 v190, v190, v191
	v_add_f32_e32 v192, v192, v193
	v_add_f32_e32 v194, v194, v195
	v_add_f32_e32 v188, v188, v190
	v_add_f32_e32 v192, v192, v194
	v_add_f32_e32 v188, v188, v192
	v_add_f32_e32 v225, v225, v188
	v_mfma_f32_16x16x32_bf16 v[188:191], v[48:51], v[140:143], v[180:183]
	v_mfma_f32_16x16x32_bf16 v[192:195], v[40:43], v[140:143], v[184:187]
	v_mfma_f32_16x16x32_bf16 v[188:191], v[44:47], v[144:147], v[188:191]
	v_mfma_f32_16x16x32_bf16 v[192:195], v[36:39], v[144:147], v[192:195]
	v_exp_f32_e32 v196, v196
	v_exp_f32_e32 v197, v197
	v_exp_f32_e32 v198, v198
	v_exp_f32_e32 v199, v199
	v_mfma_f32_16x16x32_bf16 v[112:115], v[16:19], v[246:249], v[112:115]
	v_exp_f32_e32 v200, v200
	v_exp_f32_e32 v201, v201
	v_exp_f32_e32 v202, v202
	v_exp_f32_e32 v203, v203
	v_mfma_f32_16x16x32_bf16 v[108:111], v[12:15], v[246:249], v[108:111]
	v_cvt_pk_bf16_f32 v92, v196, v197
	v_cvt_pk_bf16_f32 v93, v198, v199
	v_cvt_pk_bf16_f32 v94, v200, v201
	v_cvt_pk_bf16_f32 v95, v202, v203
	v_mfma_f32_16x16x32_bf16 v[104:107], v[8:11], v[246:249], v[104:107]
	v_add_f32_e32 v196, v196, v197
	v_add_f32_e32 v198, v198, v199
	v_add_f32_e32 v200, v200, v201
	v_add_f32_e32 v202, v202, v203
	v_mfma_f32_16x16x32_bf16 v[100:103], v[4:7], v[246:249], v[100:103]
	v_add_f32_e32 v196, v196, v198
	v_add_f32_e32 v200, v200, v202
	v_add_f32_e32 v196, v196, v200
	v_add_f32_e32 v224, v224, v196
	v_mfma_f32_16x16x32_bf16 v[196:199], v[48:51], v[132:135], v[80:83]
	v_mfma_f32_16x16x32_bf16 v[200:203], v[40:43], v[132:135], v[84:87]
	v_mfma_f32_16x16x32_bf16 v[196:199], v[44:47], v[136:139], v[196:199]
	v_mfma_f32_16x16x32_bf16 v[200:203], v[36:39], v[136:139], v[200:203]
	v_exp_f32_e32 v188, v188
	v_exp_f32_e32 v189, v189
	v_exp_f32_e32 v190, v190
	v_exp_f32_e32 v191, v191
	v_mfma_f32_16x16x32_bf16 v[128:131], v[16:19], v[92:95], v[128:131]
	v_exp_f32_e32 v192, v192
	v_exp_f32_e32 v193, v193
	v_exp_f32_e32 v194, v194
	v_exp_f32_e32 v195, v195
	v_mfma_f32_16x16x32_bf16 v[124:127], v[12:15], v[92:95], v[124:127]
	v_cvt_pk_bf16_f32 v246, v188, v189
	v_cvt_pk_bf16_f32 v247, v190, v191
	v_cvt_pk_bf16_f32 v248, v192, v193
	v_cvt_pk_bf16_f32 v249, v194, v195
	v_mfma_f32_16x16x32_bf16 v[120:123], v[8:11], v[92:95], v[120:123]
	v_add_f32_e32 v188, v188, v189
	v_add_f32_e32 v190, v190, v191
	v_add_f32_e32 v192, v192, v193
	v_add_f32_e32 v194, v194, v195
	v_mfma_f32_16x16x32_bf16 v[116:119], v[4:7], v[92:95], v[116:119]
	v_add_f32_e32 v188, v188, v190
	v_add_f32_e32 v192, v192, v194
	v_add_f32_e32 v188, v188, v192
	v_add_f32_e32 v223, v223, v188
	v_exp_f32_e32 v196, v196
	v_exp_f32_e32 v197, v197
	v_exp_f32_e32 v198, v198
	v_exp_f32_e32 v199, v199
	v_mfma_f32_16x16x32_bf16 v[64:67], v[16:19], v[246:249], v[64:67]
	v_exp_f32_e32 v200, v200
	v_exp_f32_e32 v201, v201
	v_exp_f32_e32 v202, v202
	v_exp_f32_e32 v203, v203
	v_mfma_f32_16x16x32_bf16 v[60:63], v[12:15], v[246:249], v[60:63]
	v_cvt_pk_bf16_f32 v92, v196, v197
	v_cvt_pk_bf16_f32 v93, v198, v199
	v_cvt_pk_bf16_f32 v94, v200, v201
	v_cvt_pk_bf16_f32 v95, v202, v203
	v_mfma_f32_16x16x32_bf16 v[56:59], v[8:11], v[246:249], v[56:59]
	v_add_f32_e32 v196, v196, v197
	v_add_f32_e32 v198, v198, v199
	v_add_f32_e32 v200, v200, v201
	v_add_f32_e32 v202, v202, v203
	v_mfma_f32_16x16x32_bf16 v[52:55], v[4:7], v[246:249], v[52:55]
	v_add_f32_e32 v196, v196, v198
	v_add_f32_e32 v200, v200, v202
	v_add_f32_e32 v196, v196, v200
	v_add_f32_e32 v222, v222, v196
	s_waitcnt lgkmcnt(0)
	v_sub_f32_e32 v204, v204, v239
	v_sub_f32_e32 v205, v205, v239
	v_sub_f32_e32 v206, v206, v239
	v_mfma_f32_16x16x32_bf16 v[96:99], v[16:19], v[92:95], v[96:99]
	v_sub_f32_e32 v207, v207, v239
	v_sub_f32_e32 v208, v208, v239
	v_sub_f32_e32 v209, v209, v239
	v_mfma_f32_16x16x32_bf16 v[88:91], v[12:15], v[92:95], v[88:91]
	v_sub_f32_e32 v210, v210, v239
	v_sub_f32_e32 v211, v211, v239
	v_cndmask_b32_e64 v204, v238, v204, s[0:1]
	v_mfma_f32_16x16x32_bf16 v[72:75], v[8:11], v[92:95], v[72:75]
	v_cndmask_b32_e64 v205, v238, v205, s[6:7]
	v_cndmask_b32_e64 v206, v238, v206, s[8:9]
	v_cndmask_b32_e64 v207, v238, v207, s[10:11]
	v_mfma_f32_16x16x32_bf16 v[68:71], v[4:7], v[92:95], v[68:71]
	v_cndmask_b32_e64 v208, v238, v208, s[12:13]
	v_cndmask_b32_e64 v209, v238, v209, s[14:15]
	v_cndmask_b32_e64 v210, v238, v210, s[16:17]
	v_cndmask_b32_e64 v211, v238, v211, s[18:19]
	v_add_u32_e32 v240, 0x100, v240
	s_add_u32 s92, s92, 1
	s_add_u32 s63, s63, 1
	s_and_b32 s63, s63, 3
	s_sub_i32 s80, s92, s60
	s_sub_i32 s89, s92, s76
	s_cmp_lt_i32 s80, 0
	s_cselect_b32 s89, s92, s89
	s_max_i32 s89, s89, 0
	s_min_i32 s89, s89, 7
	s_lshr_b32 s81, s89, 1
	s_lshl_b32 s81, s81, 14
	s_add_u32 s81, s81, 0x8000
	s_and_b32 s82, s89, 1
	s_lshl_b32 s20, s82, 8
	s_add_u32 s23, s81, s20
	s_lshl_b32 s20, s82, 10
	s_add_u32 s33, s81, s20
	s_add_u32 s33, s33, 0x2000
	s_cmp_ge_i32 s80, 0
	s_cselect_b32 s20, 1, 0
	s_cmp_lt_i32 s80, s76
	s_cselect_b32 s20, s20, 0
	s_cmp_lg_u32 s20, 0
	s_cbranch_scc0 .Latt_cs12
	s_lshl_b32 s81, s63, 14
	s_add_u32 s81, s81, 0x18000
	s_lshr_b32 s20, s63, 1
	s_lshl_b32 s20, s20, 4
	s_add_u32 s81, s81, s20
	s_add_u32 s82, s81, 0x2000
	s_cmp_eq_u32 s63, 3
	s_cselect_b32 s81, s83, s81
	s_cselect_b32 s82, s77, s82
	s_add_u32 s23, s81, s97
	s_add_u32 s33, s82, s90

.Latt_sk11:
	v_add_u32_e32 v251, s23, v233
	v_add_u32_e32 v253, s33, v234
	ds_read_b128 v[48:51], v251 offset:0
	ds_read_b128 v[40:43], v251 offset:4096
	ds_read_b128 v[44:47], v251 offset:2048
	ds_read_b128 v[36:39], v251 offset:6144
	ds_read_b128 v[16:19], v253 offset:0
	ds_read_b128 v[12:15], v253 offset:2048
	ds_read_b128 v[8:11], v253 offset:4096
	ds_read_b128 v[4:7], v253 offset:6144
	v_mfma_f32_16x16x32_bf16 v[188:191], v[176:179], v[156:159], v[212:215]
	v_mfma_f32_16x16x32_bf16 v[192:195], v[168:171], v[156:159], v[242:245]
	v_mfma_f32_16x16x32_bf16 v[188:191], v[172:175], v[160:163], v[188:191]
	v_mfma_f32_16x16x32_bf16 v[192:195], v[164:167], v[160:163], v[192:195]
	ds_read2_b32 v[212:213], v240 offset0:0 offset1:1
	ds_read2_b32 v[214:215], v240 offset0:2 offset1:3
	ds_read2_b32 v[242:243], v240 offset0:4 offset1:5
	ds_read2_b32 v[244:245], v240 offset0:6 offset1:7
	v_mfma_f32_16x16x32_bf16 v[196:199], v[176:179], v[148:151], v[180:183]
	v_mfma_f32_16x16x32_bf16 v[200:203], v[168:171], v[148:151], v[184:187]
	v_mfma_f32_16x16x32_bf16 v[196:199], v[172:175], v[152:155], v[196:199]
	v_mfma_f32_16x16x32_bf16 v[200:203], v[164:167], v[152:155], v[200:203]
	v_exp_f32_e32 v188, v188
	v_exp_f32_e32 v189, v189
	v_exp_f32_e32 v190, v190
	v_exp_f32_e32 v191, v191
	v_exp_f32_e32 v192, v192
	v_exp_f32_e32 v193, v193
	v_exp_f32_e32 v194, v194
	v_exp_f32_e32 v195, v195
	v_cvt_pk_bf16_f32 v246, v188, v189
	v_cvt_pk_bf16_f32 v247, v190, v191
	v_cvt_pk_bf16_f32 v248, v192, v193
	v_cvt_pk_bf16_f32 v249, v194, v195
	v_add_f32_e32 v188, v188, v189
	v_add_f32_e32 v190, v190, v191
	v_add_f32_e32 v192, v192, v193
	v_add_f32_e32 v194, v194, v195
	v_add_f32_e32 v188, v188, v190
	v_add_f32_e32 v192, v192, v194
	v_add_f32_e32 v188, v188, v192
	v_add_f32_e32 v225, v225, v188
	v_mfma_f32_16x16x32_bf16 v[188:191], v[176:179], v[140:143], v[80:83]
	v_mfma_f32_16x16x32_bf16 v[192:195], v[168:171], v[140:143], v[84:87]
	v_mfma_f32_16x16x32_bf16 v[188:191], v[172:175], v[144:147], v[188:191]
	v_mfma_f32_16x16x32_bf16 v[192:195], v[164:167], v[144:147], v[192:195]
	v_exp_f32_e32 v196, v196
	v_exp_f32_e32 v197, v197
	v_exp_f32_e32 v198, v198
	v_exp_f32_e32 v199, v199
	v_mfma_f32_16x16x32_bf16 v[112:115], v[32:35], v[246:249], v[112:115]
	v_exp_f32_e32 v200, v200
	v_exp_f32_e32 v201, v201
	v_exp_f32_e32 v202, v202
	v_exp_f32_e32 v203, v203
	v_mfma_f32_16x16x32_bf16 v[108:111], v[28:31], v[246:249], v[108:111]
	v_cvt_pk_bf16_f32 v92, v196, v197
	v_cvt_pk_bf16_f32 v93, v198, v199
	v_cvt_pk_bf16_f32 v94, v200, v201
	v_cvt_pk_bf16_f32 v95, v202, v203
	v_mfma_f32_16x16x32_bf16 v[104:107], v[24:27], v[246:249], v[104:107]
	v_add_f32_e32 v196, v196, v197
	v_add_f32_e32 v198, v198, v199
	v_add_f32_e32 v200, v200, v201
	v_add_f32_e32 v202, v202, v203
	v_mfma_f32_16x16x32_bf16 v[100:103], v[20:23], v[246:249], v[100:103]
	v_add_f32_e32 v196, v196, v198
	v_add_f32_e32 v200, v200, v202
	v_add_f32_e32 v196, v196, v200
	v_add_f32_e32 v224, v224, v196
	v_mfma_f32_16x16x32_bf16 v[196:199], v[176:179], v[132:135], v[204:207]
	v_mfma_f32_16x16x32_bf16 v[200:203], v[168:171], v[132:135], v[208:211]
	v_mfma_f32_16x16x32_bf16 v[196:199], v[172:175], v[136:139], v[196:199]
	v_mfma_f32_16x16x32_bf16 v[200:203], v[164:167], v[136:139], v[200:203]
	v_exp_f32_e32 v188, v188
	v_exp_f32_e32 v189, v189
	v_exp_f32_e32 v190, v190
	v_exp_f32_e32 v191, v191
	v_mfma_f32_16x16x32_bf16 v[128:131], v[32:35], v[92:95], v[128:131]
	v_exp_f32_e32 v192, v192
	v_exp_f32_e32 v193, v193
	v_exp_f32_e32 v194, v194
	v_exp_f32_e32 v195, v195
	v_mfma_f32_16x16x32_bf16 v[124:127], v[28:31], v[92:95], v[124:127]
	v_cvt_pk_bf16_f32 v246, v188, v189
	v_cvt_pk_bf16_f32 v247, v190, v191
	v_cvt_pk_bf16_f32 v248, v192, v193
	v_cvt_pk_bf16_f32 v249, v194, v195
	v_mfma_f32_16x16x32_bf16 v[120:123], v[24:27], v[92:95], v[120:123]
	v_add_f32_e32 v188, v188, v189
	v_add_f32_e32 v190, v190, v191
	v_add_f32_e32 v192, v192, v193
	v_add_f32_e32 v194, v194, v195
	v_mfma_f32_16x16x32_bf16 v[116:119], v[20:23], v[92:95], v[116:119]
	v_add_f32_e32 v188, v188, v190
	v_add_f32_e32 v192, v192, v194
	v_add_f32_e32 v188, v188, v192
	v_add_f32_e32 v223, v223, v188
	v_exp_f32_e32 v196, v196
	v_exp_f32_e32 v197, v197
	v_exp_f32_e32 v198, v198
	v_exp_f32_e32 v199, v199
	v_mfma_f32_16x16x32_bf16 v[64:67], v[32:35], v[246:249], v[64:67]
	v_exp_f32_e32 v200, v200
	v_exp_f32_e32 v201, v201
	v_exp_f32_e32 v202, v202
	v_exp_f32_e32 v203, v203
	v_mfma_f32_16x16x32_bf16 v[60:63], v[28:31], v[246:249], v[60:63]
	v_cvt_pk_bf16_f32 v92, v196, v197
	v_cvt_pk_bf16_f32 v93, v198, v199
	v_cvt_pk_bf16_f32 v94, v200, v201
	v_cvt_pk_bf16_f32 v95, v202, v203
	v_mfma_f32_16x16x32_bf16 v[56:59], v[24:27], v[246:249], v[56:59]
	v_add_f32_e32 v196, v196, v197
	v_add_f32_e32 v198, v198, v199
	v_add_f32_e32 v200, v200, v201
	v_add_f32_e32 v202, v202, v203
	v_mfma_f32_16x16x32_bf16 v[52:55], v[20:23], v[246:249], v[52:55]
	v_add_f32_e32 v196, v196, v198
	v_add_f32_e32 v200, v200, v202
	v_add_f32_e32 v196, v196, v200
	v_add_f32_e32 v222, v222, v196
	s_waitcnt lgkmcnt(0)
	v_sub_f32_e32 v212, v212, v239
	v_sub_f32_e32 v213, v213, v239
	v_sub_f32_e32 v214, v214, v239
	v_mfma_f32_16x16x32_bf16 v[96:99], v[32:35], v[92:95], v[96:99]
	v_sub_f32_e32 v215, v215, v239
	v_sub_f32_e32 v242, v242, v239
	v_sub_f32_e32 v243, v243, v239
	v_mfma_f32_16x16x32_bf16 v[88:91], v[28:31], v[92:95], v[88:91]
	v_sub_f32_e32 v244, v244, v239
	v_sub_f32_e32 v245, v245, v239
	v_cndmask_b32_e64 v212, v238, v212, s[0:1]
	v_mfma_f32_16x16x32_bf16 v[72:75], v[24:27], v[92:95], v[72:75]
	v_cndmask_b32_e64 v213, v238, v213, s[6:7]
	v_cndmask_b32_e64 v214, v238, v214, s[8:9]
	v_cndmask_b32_e64 v215, v238, v215, s[10:11]
	v_mfma_f32_16x16x32_bf16 v[68:71], v[20:23], v[92:95], v[68:71]
	v_cndmask_b32_e64 v242, v238, v242, s[12:13]
	v_cndmask_b32_e64 v243, v238, v243, s[14:15]
	v_cndmask_b32_e64 v244, v238, v244, s[16:17]
	v_cndmask_b32_e64 v245, v238, v245, s[18:19]
	v_add_u32_e32 v240, 0x100, v240
	s_add_u32 s92, s92, 1
	s_add_u32 s63, s63, 1
	s_and_b32 s63, s63, 3
	s_sub_i32 s80, s92, s60
	s_sub_i32 s89, s92, s76
	s_cmp_lt_i32 s80, 0
	s_cselect_b32 s89, s92, s89
	s_max_i32 s89, s89, 0
	s_min_i32 s89, s89, 7
	s_lshr_b32 s81, s89, 1
	s_lshl_b32 s81, s81, 14
	s_add_u32 s81, s81, 0x8000
	s_and_b32 s82, s89, 1
	s_lshl_b32 s20, s82, 8
	s_add_u32 s23, s81, s20
	s_lshl_b32 s20, s82, 10
	s_add_u32 s33, s81, s20
	s_add_u32 s33, s33, 0x2000
	s_cmp_ge_i32 s80, 0
	s_cselect_b32 s20, 1, 0
	s_cmp_lt_i32 s80, s76
	s_cselect_b32 s20, s20, 0
	s_cmp_lg_u32 s20, 0
	s_cbranch_scc0 .Latt_cs14
	s_lshl_b32 s81, s63, 14
	s_add_u32 s81, s81, 0x18000
	s_lshr_b32 s20, s63, 1
	s_lshl_b32 s20, s20, 4
	s_add_u32 s81, s81, s20
	s_add_u32 s82, s81, 0x2000
	s_cmp_eq_u32 s63, 3
	s_cselect_b32 s81, s83, s81
	s_cselect_b32 s82, s77, s82
	s_add_u32 s23, s81, s97
	s_add_u32 s33, s82, s90
.Latt_cs14:
	s_waitcnt lgkmcnt(0)
	v_add_u32_e32 v251, s23, v233
	v_add_u32_e32 v253, s33, v234
	ds_read_b128 v[176:179], v251 offset:0
	ds_read_b128 v[168:171], v251 offset:4096
	ds_read_b128 v[172:175], v251 offset:2048
	ds_read_b128 v[164:167], v251 offset:6144
	ds_read_b128 v[32:35], v253 offset:0
	ds_read_b128 v[28:31], v253 offset:2048
	ds_read_b128 v[24:27], v253 offset:4096
	ds_read_b128 v[20:23], v253 offset:6144
	v_mfma_f32_16x16x32_bf16 v[188:191], v[48:51], v[156:159], v[180:183]
	v_mfma_f32_16x16x32_bf16 v[192:195], v[40:43], v[156:159], v[184:187]
	v_mfma_f32_16x16x32_bf16 v[188:191], v[44:47], v[160:163], v[188:191]
	v_mfma_f32_16x16x32_bf16 v[192:195], v[36:39], v[160:163], v[192:195]
	ds_read2_b32 v[180:181], v240 offset0:0 offset1:1
	ds_read2_b32 v[182:183], v240 offset0:2 offset1:3
	ds_read2_b32 v[184:185], v240 offset0:4 offset1:5
	ds_read2_b32 v[186:187], v240 offset0:6 offset1:7
	v_mfma_f32_16x16x32_bf16 v[196:199], v[48:51], v[148:151], v[80:83]
	v_mfma_f32_16x16x32_bf16 v[200:203], v[40:43], v[148:151], v[84:87]
	v_mfma_f32_16x16x32_bf16 v[196:199], v[44:47], v[152:155], v[196:199]
	v_mfma_f32_16x16x32_bf16 v[200:203], v[36:39], v[152:155], v[200:203]
	v_exp_f32_e32 v188, v188
	v_exp_f32_e32 v189, v189
	v_exp_f32_e32 v190, v190
	v_exp_f32_e32 v191, v191
	v_exp_f32_e32 v192, v192
	v_exp_f32_e32 v193, v193
	v_exp_f32_e32 v194, v194
	v_exp_f32_e32 v195, v195
	v_cvt_pk_bf16_f32 v246, v188, v189
	v_cvt_pk_bf16_f32 v247, v190, v191
	v_cvt_pk_bf16_f32 v248, v192, v193
	v_cvt_pk_bf16_f32 v249, v194, v195
	v_add_f32_e32 v188, v188, v189
	v_add_f32_e32 v190, v190, v191
	v_add_f32_e32 v192, v192, v193
	v_add_f32_e32 v194, v194, v195
	v_add_f32_e32 v188, v188, v190
	v_add_f32_e32 v192, v192, v194
	v_add_f32_e32 v188, v188, v192
	v_add_f32_e32 v225, v225, v188
	v_mfma_f32_16x16x32_bf16 v[188:191], v[48:51], v[140:143], v[204:207]
	v_mfma_f32_16x16x32_bf16 v[192:195], v[40:43], v[140:143], v[208:211]
	v_mfma_f32_16x16x32_bf16 v[188:191], v[44:47], v[144:147], v[188:191]
	v_mfma_f32_16x16x32_bf16 v[192:195], v[36:39], v[144:147], v[192:195]
	v_exp_f32_e32 v196, v196
	v_exp_f32_e32 v197, v197
	v_exp_f32_e32 v198, v198
	v_exp_f32_e32 v199, v199
	v_mfma_f32_16x16x32_bf16 v[112:115], v[16:19], v[246:249], v[112:115]
	v_exp_f32_e32 v200, v200
	v_exp_f32_e32 v201, v201
	v_exp_f32_e32 v202, v202
	v_exp_f32_e32 v203, v203
	v_mfma_f32_16x16x32_bf16 v[108:111], v[12:15], v[246:249], v[108:111]
	v_cvt_pk_bf16_f32 v92, v196, v197
	v_cvt_pk_bf16_f32 v93, v198, v199
	v_cvt_pk_bf16_f32 v94, v200, v201
	v_cvt_pk_bf16_f32 v95, v202, v203
	v_mfma_f32_16x16x32_bf16 v[104:107], v[8:11], v[246:249], v[104:107]
	v_add_f32_e32 v196, v196, v197
	v_add_f32_e32 v198, v198, v199
	v_add_f32_e32 v200, v200, v201
	v_add_f32_e32 v202, v202, v203
	v_mfma_f32_16x16x32_bf16 v[100:103], v[4:7], v[246:249], v[100:103]
	v_add_f32_e32 v196, v196, v198
	v_add_f32_e32 v200, v200, v202
	v_add_f32_e32 v196, v196, v200
	v_add_f32_e32 v224, v224, v196
	v_mfma_f32_16x16x32_bf16 v[196:199], v[48:51], v[132:135], v[212:215]
	v_mfma_f32_16x16x32_bf16 v[200:203], v[40:43], v[132:135], v[242:245]
	v_mfma_f32_16x16x32_bf16 v[196:199], v[44:47], v[136:139], v[196:199]
	v_mfma_f32_16x16x32_bf16 v[200:203], v[36:39], v[136:139], v[200:203]
	v_exp_f32_e32 v188, v188
	v_exp_f32_e32 v189, v189
	v_exp_f32_e32 v190, v190
	v_exp_f32_e32 v191, v191
	v_mfma_f32_16x16x32_bf16 v[128:131], v[16:19], v[92:95], v[128:131]
	v_exp_f32_e32 v192, v192
	v_exp_f32_e32 v193, v193
	v_exp_f32_e32 v194, v194
	v_exp_f32_e32 v195, v195
	v_mfma_f32_16x16x32_bf16 v[124:127], v[12:15], v[92:95], v[124:127]
	v_cvt_pk_bf16_f32 v246, v188, v189
	v_cvt_pk_bf16_f32 v247, v190, v191
	v_cvt_pk_bf16_f32 v248, v192, v193
	v_cvt_pk_bf16_f32 v249, v194, v195
	v_mfma_f32_16x16x32_bf16 v[120:123], v[8:11], v[92:95], v[120:123]
	v_add_f32_e32 v188, v188, v189
	v_add_f32_e32 v190, v190, v191
	v_add_f32_e32 v192, v192, v193
	v_add_f32_e32 v194, v194, v195
	v_mfma_f32_16x16x32_bf16 v[116:119], v[4:7], v[92:95], v[116:119]
	v_add_f32_e32 v188, v188, v190
	v_add_f32_e32 v192, v192, v194
	v_add_f32_e32 v188, v188, v192
	v_add_f32_e32 v223, v223, v188
	v_exp_f32_e32 v196, v196
	v_exp_f32_e32 v197, v197
	v_exp_f32_e32 v198, v198
	v_exp_f32_e32 v199, v199
	v_mfma_f32_16x16x32_bf16 v[64:67], v[16:19], v[246:249], v[64:67]
	v_exp_f32_e32 v200, v200
	v_exp_f32_e32 v201, v201
	v_exp_f32_e32 v202, v202
	v_exp_f32_e32 v203, v203
	v_mfma_f32_16x16x32_bf16 v[60:63], v[12:15], v[246:249], v[60:63]
	v_cvt_pk_bf16_f32 v92, v196, v197
	v_cvt_pk_bf16_f32 v93, v198, v199
	v_cvt_pk_bf16_f32 v94, v200, v201
	v_cvt_pk_bf16_f32 v95, v202, v203
	v_mfma_f32_16x16x32_bf16 v[56:59], v[8:11], v[246:249], v[56:59]
	v_add_f32_e32 v196, v196, v197
	v_add_f32_e32 v198, v198, v199
	v_add_f32_e32 v200, v200, v201
	v_add_f32_e32 v202, v202, v203
	v_mfma_f32_16x16x32_bf16 v[52:55], v[4:7], v[246:249], v[52:55]
	v_add_f32_e32 v196, v196, v198
	v_add_f32_e32 v200, v200, v202
	v_add_f32_e32 v196, v196, v200
	v_add_f32_e32 v222, v222, v196
	s_waitcnt lgkmcnt(0)
	v_sub_f32_e32 v180, v180, v239
	v_sub_f32_e32 v181, v181, v239
	v_sub_f32_e32 v182, v182, v239
	v_mfma_f32_16x16x32_bf16 v[96:99], v[16:19], v[92:95], v[96:99]
	v_sub_f32_e32 v183, v183, v239
	v_sub_f32_e32 v184, v184, v239
	v_sub_f32_e32 v185, v185, v239
	v_mfma_f32_16x16x32_bf16 v[88:91], v[12:15], v[92:95], v[88:91]
	v_sub_f32_e32 v186, v186, v239
	v_sub_f32_e32 v187, v187, v239
	v_cndmask_b32_e64 v180, v238, v180, s[0:1]
	v_mfma_f32_16x16x32_bf16 v[72:75], v[8:11], v[92:95], v[72:75]
	v_cndmask_b32_e64 v181, v238, v181, s[6:7]
	v_cndmask_b32_e64 v182, v238, v182, s[8:9]
	v_cndmask_b32_e64 v183, v238, v183, s[10:11]
	v_mfma_f32_16x16x32_bf16 v[68:71], v[4:7], v[92:95], v[68:71]
	v_cndmask_b32_e64 v184, v238, v184, s[12:13]
	v_cndmask_b32_e64 v185, v238, v185, s[14:15]
	v_cndmask_b32_e64 v186, v238, v186, s[16:17]
	v_cndmask_b32_e64 v187, v238, v187, s[18:19]
	v_add_u32_e32 v240, 0x100, v240
	s_add_u32 s92, s92, 1
	s_add_u32 s63, s63, 1
	s_and_b32 s63, s63, 3
	s_sub_i32 s80, s92, s60
	s_sub_i32 s89, s92, s76
	s_cmp_lt_i32 s80, 0
	s_cselect_b32 s89, s92, s89
	s_max_i32 s89, s89, 0
	s_min_i32 s89, s89, 7
	s_lshr_b32 s81, s89, 1
	s_lshl_b32 s81, s81, 14
	s_add_u32 s81, s81, 0x8000
	s_and_b32 s82, s89, 1
	s_lshl_b32 s20, s82, 8
	s_add_u32 s23, s81, s20
	s_lshl_b32 s20, s82, 10
	s_add_u32 s33, s81, s20
	s_add_u32 s33, s33, 0x2000
	s_cmp_ge_i32 s80, 0
	s_cselect_b32 s20, 1, 0
	s_cmp_lt_i32 s80, s76
	s_cselect_b32 s20, s20, 0
	s_cmp_lg_u32 s20, 0
	s_cbranch_scc0 .Latt_cs16
	s_lshl_b32 s81, s63, 14
	s_add_u32 s81, s81, 0x18000
	s_lshr_b32 s20, s63, 1
	s_lshl_b32 s20, s20, 4
	s_add_u32 s81, s81, s20
	s_add_u32 s82, s81, 0x2000
	s_cmp_eq_u32 s63, 3
	s_cselect_b32 s81, s83, s81
	s_cselect_b32 s82, s77, s82
	s_add_u32 s23, s81, s97
	s_add_u32 s33, s82, s90

.Latt_sk15:
	v_add_u32_e32 v251, s23, v233
	v_add_u32_e32 v253, s33, v234
	ds_read_b128 v[48:51], v251 offset:0
	ds_read_b128 v[40:43], v251 offset:4096
	ds_read_b128 v[44:47], v251 offset:2048
	ds_read_b128 v[36:39], v251 offset:6144
	ds_read_b128 v[16:19], v253 offset:0
	ds_read_b128 v[12:15], v253 offset:2048
	ds_read_b128 v[8:11], v253 offset:4096
	ds_read_b128 v[4:7], v253 offset:6144
	v_mfma_f32_16x16x32_bf16 v[188:191], v[176:179], v[156:159], v[80:83]
	v_mfma_f32_16x16x32_bf16 v[192:195], v[168:171], v[156:159], v[84:87]
	v_mfma_f32_16x16x32_bf16 v[188:191], v[172:175], v[160:163], v[188:191]
	v_mfma_f32_16x16x32_bf16 v[192:195], v[164:167], v[160:163], v[192:195]
	ds_read2_b32 v[80:81], v240 offset0:0 offset1:1
	ds_read2_b32 v[82:83], v240 offset0:2 offset1:3
	ds_read2_b32 v[84:85], v240 offset0:4 offset1:5
	ds_read2_b32 v[86:87], v240 offset0:6 offset1:7
	v_mfma_f32_16x16x32_bf16 v[196:199], v[176:179], v[148:151], v[204:207]
	v_mfma_f32_16x16x32_bf16 v[200:203], v[168:171], v[148:151], v[208:211]
	v_mfma_f32_16x16x32_bf16 v[196:199], v[172:175], v[152:155], v[196:199]
	v_mfma_f32_16x16x32_bf16 v[200:203], v[164:167], v[152:155], v[200:203]
	v_exp_f32_e32 v188, v188
	v_exp_f32_e32 v189, v189
	v_exp_f32_e32 v190, v190
	v_exp_f32_e32 v191, v191
	v_exp_f32_e32 v192, v192
	v_exp_f32_e32 v193, v193
	v_exp_f32_e32 v194, v194
	v_exp_f32_e32 v195, v195
	v_cvt_pk_bf16_f32 v246, v188, v189
	v_cvt_pk_bf16_f32 v247, v190, v191
	v_cvt_pk_bf16_f32 v248, v192, v193
	v_cvt_pk_bf16_f32 v249, v194, v195
	v_add_f32_e32 v188, v188, v189
	v_add_f32_e32 v190, v190, v191
	v_add_f32_e32 v192, v192, v193
	v_add_f32_e32 v194, v194, v195
	v_add_f32_e32 v188, v188, v190
	v_add_f32_e32 v192, v192, v194
	v_add_f32_e32 v188, v188, v192
	v_add_f32_e32 v225, v225, v188
	v_mfma_f32_16x16x32_bf16 v[188:191], v[176:179], v[140:143], v[212:215]
	v_mfma_f32_16x16x32_bf16 v[192:195], v[168:171], v[140:143], v[242:245]
	v_mfma_f32_16x16x32_bf16 v[188:191], v[172:175], v[144:147], v[188:191]
	v_mfma_f32_16x16x32_bf16 v[192:195], v[164:167], v[144:147], v[192:195]
	v_exp_f32_e32 v196, v196
	v_exp_f32_e32 v197, v197
	v_exp_f32_e32 v198, v198
	v_exp_f32_e32 v199, v199
	v_mfma_f32_16x16x32_bf16 v[112:115], v[32:35], v[246:249], v[112:115]
	v_exp_f32_e32 v200, v200
	v_exp_f32_e32 v201, v201
	v_exp_f32_e32 v202, v202
	v_exp_f32_e32 v203, v203
	v_mfma_f32_16x16x32_bf16 v[108:111], v[28:31], v[246:249], v[108:111]
	v_cvt_pk_bf16_f32 v92, v196, v197
	v_cvt_pk_bf16_f32 v93, v198, v199
	v_cvt_pk_bf16_f32 v94, v200, v201
	v_cvt_pk_bf16_f32 v95, v202, v203
	v_mfma_f32_16x16x32_bf16 v[104:107], v[24:27], v[246:249], v[104:107]
	v_add_f32_e32 v196, v196, v197
	v_add_f32_e32 v198, v198, v199
	v_add_f32_e32 v200, v200, v201
	v_add_f32_e32 v202, v202, v203
	v_mfma_f32_16x16x32_bf16 v[100:103], v[20:23], v[246:249], v[100:103]
	v_add_f32_e32 v196, v196, v198
	v_add_f32_e32 v200, v200, v202
	v_add_f32_e32 v196, v196, v200
	v_add_f32_e32 v224, v224, v196
	v_mfma_f32_16x16x32_bf16 v[196:199], v[176:179], v[132:135], v[180:183]
	v_mfma_f32_16x16x32_bf16 v[200:203], v[168:171], v[132:135], v[184:187]
	v_mfma_f32_16x16x32_bf16 v[196:199], v[172:175], v[136:139], v[196:199]
	v_mfma_f32_16x16x32_bf16 v[200:203], v[164:167], v[136:139], v[200:203]
	v_exp_f32_e32 v188, v188
	v_exp_f32_e32 v189, v189
	v_exp_f32_e32 v190, v190
	v_exp_f32_e32 v191, v191
	v_mfma_f32_16x16x32_bf16 v[128:131], v[32:35], v[92:95], v[128:131]
	v_exp_f32_e32 v192, v192
	v_exp_f32_e32 v193, v193
	v_exp_f32_e32 v194, v194
	v_exp_f32_e32 v195, v195
	v_mfma_f32_16x16x32_bf16 v[124:127], v[28:31], v[92:95], v[124:127]
	v_cvt_pk_bf16_f32 v246, v188, v189
	v_cvt_pk_bf16_f32 v247, v190, v191
	v_cvt_pk_bf16_f32 v248, v192, v193
	v_cvt_pk_bf16_f32 v249, v194, v195
	v_mfma_f32_16x16x32_bf16 v[120:123], v[24:27], v[92:95], v[120:123]
	v_add_f32_e32 v188, v188, v189
	v_add_f32_e32 v190, v190, v191
	v_add_f32_e32 v192, v192, v193
	v_add_f32_e32 v194, v194, v195
	v_mfma_f32_16x16x32_bf16 v[116:119], v[20:23], v[92:95], v[116:119]
	v_add_f32_e32 v188, v188, v190
	v_add_f32_e32 v192, v192, v194
	v_add_f32_e32 v188, v188, v192
	v_add_f32_e32 v223, v223, v188
	v_exp_f32_e32 v196, v196
	v_exp_f32_e32 v197, v197
	v_exp_f32_e32 v198, v198
	v_exp_f32_e32 v199, v199
	v_mfma_f32_16x16x32_bf16 v[64:67], v[32:35], v[246:249], v[64:67]
	v_exp_f32_e32 v200, v200
	v_exp_f32_e32 v201, v201
	v_exp_f32_e32 v202, v202
	v_exp_f32_e32 v203, v203
	v_mfma_f32_16x16x32_bf16 v[60:63], v[28:31], v[246:249], v[60:63]
	v_cvt_pk_bf16_f32 v92, v196, v197
	v_cvt_pk_bf16_f32 v93, v198, v199
	v_cvt_pk_bf16_f32 v94, v200, v201
	v_cvt_pk_bf16_f32 v95, v202, v203
	v_mfma_f32_16x16x32_bf16 v[56:59], v[24:27], v[246:249], v[56:59]
	v_add_f32_e32 v196, v196, v197
	v_add_f32_e32 v198, v198, v199
	v_add_f32_e32 v200, v200, v201
	v_add_f32_e32 v202, v202, v203
	v_mfma_f32_16x16x32_bf16 v[52:55], v[20:23], v[246:249], v[52:55]
	v_add_f32_e32 v196, v196, v198
	v_add_f32_e32 v200, v200, v202
	v_add_f32_e32 v196, v196, v200
	v_add_f32_e32 v222, v222, v196
	s_waitcnt lgkmcnt(0)
	v_sub_f32_e32 v80, v80, v239
	v_sub_f32_e32 v81, v81, v239
	v_sub_f32_e32 v82, v82, v239
	v_mfma_f32_16x16x32_bf16 v[96:99], v[32:35], v[92:95], v[96:99]
	v_sub_f32_e32 v83, v83, v239
	v_sub_f32_e32 v84, v84, v239
	v_sub_f32_e32 v85, v85, v239
	v_mfma_f32_16x16x32_bf16 v[88:91], v[28:31], v[92:95], v[88:91]
	v_sub_f32_e32 v86, v86, v239
	v_sub_f32_e32 v87, v87, v239
	v_cndmask_b32_e64 v80, v238, v80, s[0:1]
	v_mfma_f32_16x16x32_bf16 v[72:75], v[24:27], v[92:95], v[72:75]
	v_cndmask_b32_e64 v81, v238, v81, s[6:7]
	v_cndmask_b32_e64 v82, v238, v82, s[8:9]
	v_cndmask_b32_e64 v83, v238, v83, s[10:11]
	v_mfma_f32_16x16x32_bf16 v[68:71], v[20:23], v[92:95], v[68:71]
	v_cndmask_b32_e64 v84, v238, v84, s[12:13]
	v_cndmask_b32_e64 v85, v238, v85, s[14:15]
	v_cndmask_b32_e64 v86, v238, v86, s[16:17]
	v_cndmask_b32_e64 v87, v238, v87, s[18:19]
	v_add_u32_e32 v240, 0x100, v240
	s_add_u32 s92, s92, 1
	s_add_u32 s63, s63, 1
	s_and_b32 s63, s63, 3
	s_sub_i32 s80, s92, s60
	s_sub_i32 s89, s92, s76
	s_cmp_lt_i32 s80, 0
	s_cselect_b32 s89, s92, s89
	s_max_i32 s89, s89, 0
	s_min_i32 s89, s89, 7
	s_lshr_b32 s81, s89, 1
	s_lshl_b32 s81, s81, 14
	s_add_u32 s81, s81, 0x8000
	s_and_b32 s82, s89, 1
	s_lshl_b32 s20, s82, 8
	s_add_u32 s23, s81, s20
	s_lshl_b32 s20, s82, 10
	s_add_u32 s33, s81, s20
	s_add_u32 s33, s33, 0x2000
	s_cmp_ge_i32 s80, 0
	s_cselect_b32 s20, 1, 0
	s_cmp_lt_i32 s80, s76
	s_cselect_b32 s20, s20, 0
	s_cmp_lg_u32 s20, 0
	s_cbranch_scc0 .Latt_cs18
	s_lshl_b32 s81, s63, 14
	s_add_u32 s81, s81, 0x18000
	s_lshr_b32 s20, s63, 1
	s_lshl_b32 s20, s20, 4
	s_add_u32 s81, s81, s20
	s_add_u32 s82, s81, 0x2000
	s_cmp_eq_u32 s63, 3
	s_cselect_b32 s81, s83, s81
	s_cselect_b32 s82, s77, s82
	s_add_u32 s23, s81, s97
	s_add_u32 s33, s82, s90
.Latt_cs18:
	s_waitcnt lgkmcnt(0)
	v_add_u32_e32 v251, s23, v233
	v_add_u32_e32 v253, s33, v234
	ds_read_b128 v[176:179], v251 offset:0
	ds_read_b128 v[168:171], v251 offset:4096
	ds_read_b128 v[172:175], v251 offset:2048
	ds_read_b128 v[164:167], v251 offset:6144
	ds_read_b128 v[32:35], v253 offset:0
	ds_read_b128 v[28:31], v253 offset:2048
	ds_read_b128 v[24:27], v253 offset:4096
	ds_read_b128 v[20:23], v253 offset:6144
	v_mfma_f32_16x16x32_bf16 v[188:191], v[48:51], v[156:159], v[204:207]
	v_mfma_f32_16x16x32_bf16 v[192:195], v[40:43], v[156:159], v[208:211]
	v_mfma_f32_16x16x32_bf16 v[188:191], v[44:47], v[160:163], v[188:191]
	v_mfma_f32_16x16x32_bf16 v[192:195], v[36:39], v[160:163], v[192:195]
	v_mfma_f32_16x16x32_bf16 v[196:199], v[48:51], v[148:151], v[212:215]
	v_mfma_f32_16x16x32_bf16 v[200:203], v[40:43], v[148:151], v[242:245]
	v_mfma_f32_16x16x32_bf16 v[196:199], v[44:47], v[152:155], v[196:199]
	v_mfma_f32_16x16x32_bf16 v[200:203], v[36:39], v[152:155], v[200:203]
	s_nop 2
	v_exp_f32_e32 v188, v188
	v_exp_f32_e32 v189, v189
	v_exp_f32_e32 v190, v190
	v_exp_f32_e32 v191, v191
	v_exp_f32_e32 v192, v192
	v_exp_f32_e32 v193, v193
	v_exp_f32_e32 v194, v194
	v_exp_f32_e32 v195, v195
	v_cvt_pk_bf16_f32 v246, v188, v189
	v_cvt_pk_bf16_f32 v247, v190, v191
	v_cvt_pk_bf16_f32 v248, v192, v193
	v_cvt_pk_bf16_f32 v249, v194, v195
	v_add_f32_e32 v188, v188, v189
	v_add_f32_e32 v190, v190, v191
	v_add_f32_e32 v192, v192, v193
	v_add_f32_e32 v194, v194, v195
	v_add_f32_e32 v188, v188, v190
	v_add_f32_e32 v192, v192, v194
	v_add_f32_e32 v188, v188, v192
	v_add_f32_e32 v225, v225, v188
	v_mfma_f32_16x16x32_bf16 v[188:191], v[48:51], v[140:143], v[180:183]
	v_mfma_f32_16x16x32_bf16 v[192:195], v[40:43], v[140:143], v[184:187]
	v_mfma_f32_16x16x32_bf16 v[188:191], v[44:47], v[144:147], v[188:191]
	v_mfma_f32_16x16x32_bf16 v[192:195], v[36:39], v[144:147], v[192:195]
	v_exp_f32_e32 v196, v196
	v_exp_f32_e32 v197, v197
	v_exp_f32_e32 v198, v198
	v_exp_f32_e32 v199, v199
	v_mfma_f32_16x16x32_bf16 v[112:115], v[16:19], v[246:249], v[112:115]
	v_exp_f32_e32 v200, v200
	v_exp_f32_e32 v201, v201
	v_exp_f32_e32 v202, v202
	v_exp_f32_e32 v203, v203
	v_mfma_f32_16x16x32_bf16 v[108:111], v[12:15], v[246:249], v[108:111]
	v_cvt_pk_bf16_f32 v92, v196, v197
	v_cvt_pk_bf16_f32 v93, v198, v199
	v_cvt_pk_bf16_f32 v94, v200, v201
	v_cvt_pk_bf16_f32 v95, v202, v203
	v_mfma_f32_16x16x32_bf16 v[104:107], v[8:11], v[246:249], v[104:107]
	v_add_f32_e32 v196, v196, v197
	v_add_f32_e32 v198, v198, v199
	v_add_f32_e32 v200, v200, v201
	v_add_f32_e32 v202, v202, v203
	v_mfma_f32_16x16x32_bf16 v[100:103], v[4:7], v[246:249], v[100:103]
	v_add_f32_e32 v196, v196, v198
	v_add_f32_e32 v200, v200, v202
	v_add_f32_e32 v196, v196, v200
	v_add_f32_e32 v224, v224, v196
	v_mfma_f32_16x16x32_bf16 v[196:199], v[48:51], v[132:135], v[80:83]
	v_mfma_f32_16x16x32_bf16 v[200:203], v[40:43], v[132:135], v[84:87]
	v_mfma_f32_16x16x32_bf16 v[196:199], v[44:47], v[136:139], v[196:199]
	v_mfma_f32_16x16x32_bf16 v[200:203], v[36:39], v[136:139], v[200:203]
	v_exp_f32_e32 v188, v188
	v_exp_f32_e32 v189, v189
	v_exp_f32_e32 v190, v190
	v_exp_f32_e32 v191, v191
	v_mfma_f32_16x16x32_bf16 v[128:131], v[16:19], v[92:95], v[128:131]
	v_exp_f32_e32 v192, v192
	v_exp_f32_e32 v193, v193
	v_exp_f32_e32 v194, v194
	v_exp_f32_e32 v195, v195
	v_mfma_f32_16x16x32_bf16 v[124:127], v[12:15], v[92:95], v[124:127]
	v_cvt_pk_bf16_f32 v246, v188, v189
	v_cvt_pk_bf16_f32 v247, v190, v191
	v_cvt_pk_bf16_f32 v248, v192, v193
	v_cvt_pk_bf16_f32 v249, v194, v195
	v_mfma_f32_16x16x32_bf16 v[120:123], v[8:11], v[92:95], v[120:123]
	v_add_f32_e32 v188, v188, v189
	v_add_f32_e32 v190, v190, v191
	v_add_f32_e32 v192, v192, v193
	v_add_f32_e32 v194, v194, v195
	v_mfma_f32_16x16x32_bf16 v[116:119], v[4:7], v[92:95], v[116:119]
	v_add_f32_e32 v188, v188, v190
	v_add_f32_e32 v192, v192, v194
	v_add_f32_e32 v188, v188, v192
	v_add_f32_e32 v223, v223, v188
	v_exp_f32_e32 v196, v196
	v_exp_f32_e32 v197, v197
	v_exp_f32_e32 v198, v198
	v_exp_f32_e32 v199, v199
	v_mfma_f32_16x16x32_bf16 v[64:67], v[16:19], v[246:249], v[64:67]
	v_exp_f32_e32 v200, v200
	v_exp_f32_e32 v201, v201
	v_exp_f32_e32 v202, v202
	v_exp_f32_e32 v203, v203
	v_mfma_f32_16x16x32_bf16 v[60:63], v[12:15], v[246:249], v[60:63]
	v_cvt_pk_bf16_f32 v92, v196, v197
	v_cvt_pk_bf16_f32 v93, v198, v199
	v_cvt_pk_bf16_f32 v94, v200, v201
	v_cvt_pk_bf16_f32 v95, v202, v203
	v_mfma_f32_16x16x32_bf16 v[56:59], v[8:11], v[246:249], v[56:59]
	v_add_f32_e32 v196, v196, v197
	v_add_f32_e32 v198, v198, v199
	v_add_f32_e32 v200, v200, v201
	v_add_f32_e32 v202, v202, v203
	v_mfma_f32_16x16x32_bf16 v[52:55], v[4:7], v[246:249], v[52:55]
	v_add_f32_e32 v196, v196, v198
	v_add_f32_e32 v200, v200, v202
	v_add_f32_e32 v196, v196, v200
	v_add_f32_e32 v222, v222, v196
	v_mfma_f32_16x16x32_bf16 v[96:99], v[16:19], v[92:95], v[96:99]
	v_mfma_f32_16x16x32_bf16 v[88:91], v[12:15], v[92:95], v[88:91]
	v_mfma_f32_16x16x32_bf16 v[72:75], v[8:11], v[92:95], v[72:75]
	v_mfma_f32_16x16x32_bf16 v[68:71], v[4:7], v[92:95], v[68:71]
	v_add_u32_e32 v240, 0x100, v240
	s_add_u32 s92, s92, 1
	s_add_u32 s63, s63, 1
	s_and_b32 s63, s63, 3
	s_sub_i32 s80, s92, s60
	s_sub_i32 s89, s92, s76
	s_cmp_lt_i32 s80, 0
	s_cselect_b32 s89, s92, s89
	s_max_i32 s89, s89, 0
	s_min_i32 s89, s89, 7
	s_lshr_b32 s81, s89, 1
	s_lshl_b32 s81, s81, 14
	s_add_u32 s81, s81, 0x8000
	s_and_b32 s82, s89, 1
	s_lshl_b32 s20, s82, 8
	s_add_u32 s23, s81, s20
	s_lshl_b32 s20, s82, 10
	s_add_u32 s33, s81, s20
	s_add_u32 s33, s33, 0x2000
	s_cmp_ge_i32 s80, 0
	s_cselect_b32 s20, 1, 0
	s_cmp_lt_i32 s80, s76
	s_cselect_b32 s20, s20, 0
	s_cmp_lg_u32 s20, 0
	s_cbranch_scc0 .Latt_cs20
	s_lshl_b32 s81, s63, 14
	s_add_u32 s81, s81, 0x18000
	s_lshr_b32 s20, s63, 1
	s_lshl_b32 s20, s20, 4
	s_add_u32 s81, s81, s20
	s_add_u32 s82, s81, 0x2000
	s_cmp_eq_u32 s63, 3
	s_cselect_b32 s81, s83, s81
	s_cselect_b32 s82, s77, s82
	s_add_u32 s23, s81, s97
	s_add_u32 s33, s82, s90

.Latt_sk19:
	v_add_u32_e32 v251, s23, v233
	v_add_u32_e32 v253, s33, v234
	ds_read_b128 v[48:51], v251 offset:0
	ds_read_b128 v[40:43], v251 offset:4096
	ds_read_b128 v[44:47], v251 offset:2048
	ds_read_b128 v[36:39], v251 offset:6144
	ds_read_b128 v[16:19], v253 offset:0
	ds_read_b128 v[12:15], v253 offset:2048
	ds_read_b128 v[8:11], v253 offset:4096
	ds_read_b128 v[4:7], v253 offset:6144
	v_mfma_f32_16x16x32_bf16 v[188:191], v[176:179], v[156:159], v[212:215]
	v_mfma_f32_16x16x32_bf16 v[192:195], v[168:171], v[156:159], v[242:245]
	v_mfma_f32_16x16x32_bf16 v[188:191], v[172:175], v[160:163], v[188:191]
	v_mfma_f32_16x16x32_bf16 v[192:195], v[164:167], v[160:163], v[192:195]
	v_mfma_f32_16x16x32_bf16 v[196:199], v[176:179], v[148:151], v[180:183]
	v_mfma_f32_16x16x32_bf16 v[200:203], v[168:171], v[148:151], v[184:187]
	v_mfma_f32_16x16x32_bf16 v[196:199], v[172:175], v[152:155], v[196:199]
	v_mfma_f32_16x16x32_bf16 v[200:203], v[164:167], v[152:155], v[200:203]
	s_nop 2
	v_exp_f32_e32 v188, v188
	v_exp_f32_e32 v189, v189
	v_exp_f32_e32 v190, v190
	v_exp_f32_e32 v191, v191
	v_exp_f32_e32 v192, v192
	v_exp_f32_e32 v193, v193
	v_exp_f32_e32 v194, v194
	v_exp_f32_e32 v195, v195
	v_cvt_pk_bf16_f32 v246, v188, v189
	v_cvt_pk_bf16_f32 v247, v190, v191
	v_cvt_pk_bf16_f32 v248, v192, v193
	v_cvt_pk_bf16_f32 v249, v194, v195
	v_add_f32_e32 v188, v188, v189
	v_add_f32_e32 v190, v190, v191
	v_add_f32_e32 v192, v192, v193
	v_add_f32_e32 v194, v194, v195
	v_add_f32_e32 v188, v188, v190
	v_add_f32_e32 v192, v192, v194
	v_add_f32_e32 v188, v188, v192
	v_add_f32_e32 v225, v225, v188
	v_mfma_f32_16x16x32_bf16 v[188:191], v[176:179], v[140:143], v[80:83]
	v_mfma_f32_16x16x32_bf16 v[192:195], v[168:171], v[140:143], v[84:87]
	v_mfma_f32_16x16x32_bf16 v[188:191], v[172:175], v[144:147], v[188:191]
	v_mfma_f32_16x16x32_bf16 v[192:195], v[164:167], v[144:147], v[192:195]
	v_exp_f32_e32 v196, v196
	v_exp_f32_e32 v197, v197
	v_exp_f32_e32 v198, v198
	v_exp_f32_e32 v199, v199
	v_mfma_f32_16x16x32_bf16 v[112:115], v[32:35], v[246:249], v[112:115]
	v_exp_f32_e32 v200, v200
	v_exp_f32_e32 v201, v201
	v_exp_f32_e32 v202, v202
	v_exp_f32_e32 v203, v203
	v_mfma_f32_16x16x32_bf16 v[108:111], v[28:31], v[246:249], v[108:111]
	v_cvt_pk_bf16_f32 v92, v196, v197
	v_cvt_pk_bf16_f32 v93, v198, v199
	v_cvt_pk_bf16_f32 v94, v200, v201
	v_cvt_pk_bf16_f32 v95, v202, v203
	v_mfma_f32_16x16x32_bf16 v[104:107], v[24:27], v[246:249], v[104:107]
	v_add_f32_e32 v196, v196, v197
	v_add_f32_e32 v198, v198, v199
	v_add_f32_e32 v200, v200, v201
	v_add_f32_e32 v202, v202, v203
	v_mfma_f32_16x16x32_bf16 v[100:103], v[20:23], v[246:249], v[100:103]
	v_add_f32_e32 v196, v196, v198
	v_add_f32_e32 v200, v200, v202
	v_add_f32_e32 v196, v196, v200
	v_add_f32_e32 v224, v224, v196
	v_exp_f32_e32 v188, v188
	v_exp_f32_e32 v189, v189
	v_exp_f32_e32 v190, v190
	v_exp_f32_e32 v191, v191
	v_mfma_f32_16x16x32_bf16 v[128:131], v[32:35], v[92:95], v[128:131]
	v_exp_f32_e32 v192, v192
	v_exp_f32_e32 v193, v193
	v_exp_f32_e32 v194, v194
	v_exp_f32_e32 v195, v195
	v_mfma_f32_16x16x32_bf16 v[124:127], v[28:31], v[92:95], v[124:127]
	v_cvt_pk_bf16_f32 v246, v188, v189
	v_cvt_pk_bf16_f32 v247, v190, v191
	v_cvt_pk_bf16_f32 v248, v192, v193
	v_cvt_pk_bf16_f32 v249, v194, v195
	v_mfma_f32_16x16x32_bf16 v[120:123], v[24:27], v[92:95], v[120:123]
	v_add_f32_e32 v188, v188, v189
	v_add_f32_e32 v190, v190, v191
	v_add_f32_e32 v192, v192, v193
	v_add_f32_e32 v194, v194, v195
	v_mfma_f32_16x16x32_bf16 v[116:119], v[20:23], v[92:95], v[116:119]
	v_add_f32_e32 v188, v188, v190
	v_add_f32_e32 v192, v192, v194
	v_add_f32_e32 v188, v188, v192
	v_add_f32_e32 v223, v223, v188
	v_mfma_f32_16x16x32_bf16 v[64:67], v[32:35], v[246:249], v[64:67]
	v_mfma_f32_16x16x32_bf16 v[60:63], v[28:31], v[246:249], v[60:63]
	v_mfma_f32_16x16x32_bf16 v[56:59], v[24:27], v[246:249], v[56:59]
	v_mfma_f32_16x16x32_bf16 v[52:55], v[20:23], v[246:249], v[52:55]
	v_add_u32_e32 v240, 0x100, v240
	s_add_u32 s92, s92, 1
	s_add_u32 s63, s63, 1
	s_and_b32 s63, s63, 3
	s_sub_i32 s80, s92, s60
	s_sub_i32 s89, s92, s76
	s_cmp_lt_i32 s80, 0
	s_cselect_b32 s89, s92, s89
	s_max_i32 s89, s89, 0
	s_min_i32 s89, s89, 7
	s_lshr_b32 s81, s89, 1
	s_lshl_b32 s81, s81, 14
	s_add_u32 s81, s81, 0x8000
	s_and_b32 s82, s89, 1
	s_lshl_b32 s20, s82, 8
	s_add_u32 s23, s81, s20
	s_lshl_b32 s20, s82, 10
	s_add_u32 s33, s81, s20
	s_add_u32 s33, s33, 0x2000
	s_cmp_ge_i32 s80, 0
	s_cselect_b32 s20, 1, 0
	s_cmp_lt_i32 s80, s76
	s_cselect_b32 s20, s20, 0
	s_cmp_lg_u32 s20, 0
	s_cbranch_scc0 .Latt_cs22
	s_lshl_b32 s81, s63, 14
	s_add_u32 s81, s81, 0x18000
	s_lshr_b32 s20, s63, 1
	s_lshl_b32 s20, s20, 4
	s_add_u32 s81, s81, s20
	s_add_u32 s82, s81, 0x2000
	s_cmp_eq_u32 s63, 3
	s_cselect_b32 s81, s83, s81
	s_cselect_b32 s82, s77, s82
	s_add_u32 s23, s81, s97
	s_add_u32 s33, s82, s90
.Latt_cs22:
	s_waitcnt lgkmcnt(0)
	v_add_u32_e32 v251, s23, v233
	v_add_u32_e32 v253, s33, v234
	ds_read_b128 v[176:179], v251 offset:0
	ds_read_b128 v[168:171], v251 offset:4096
	ds_read_b128 v[172:175], v251 offset:2048
	ds_read_b128 v[164:167], v251 offset:6144
	ds_read_b128 v[32:35], v253 offset:0
	ds_read_b128 v[28:31], v253 offset:2048
	ds_read_b128 v[24:27], v253 offset:4096
	ds_read_b128 v[20:23], v253 offset:6144
	v_mfma_f32_16x16x32_bf16 v[188:191], v[48:51], v[156:159], v[180:183]
	v_mfma_f32_16x16x32_bf16 v[192:195], v[40:43], v[156:159], v[184:187]
	v_mfma_f32_16x16x32_bf16 v[188:191], v[44:47], v[160:163], v[188:191]
	v_mfma_f32_16x16x32_bf16 v[192:195], v[36:39], v[160:163], v[192:195]
	v_mfma_f32_16x16x32_bf16 v[196:199], v[48:51], v[148:151], v[80:83]
	v_mfma_f32_16x16x32_bf16 v[200:203], v[40:43], v[148:151], v[84:87]
	v_mfma_f32_16x16x32_bf16 v[196:199], v[44:47], v[152:155], v[196:199]
	v_mfma_f32_16x16x32_bf16 v[200:203], v[36:39], v[152:155], v[200:203]
	s_nop 2
	v_exp_f32_e32 v188, v188
	v_exp_f32_e32 v189, v189
	v_exp_f32_e32 v190, v190
	v_exp_f32_e32 v191, v191
	v_exp_f32_e32 v192, v192
	v_exp_f32_e32 v193, v193
	v_exp_f32_e32 v194, v194
	v_exp_f32_e32 v195, v195
	v_cvt_pk_bf16_f32 v246, v188, v189
	v_cvt_pk_bf16_f32 v247, v190, v191
	v_cvt_pk_bf16_f32 v248, v192, v193
	v_cvt_pk_bf16_f32 v249, v194, v195
	v_add_f32_e32 v188, v188, v189
	v_add_f32_e32 v190, v190, v191
	v_add_f32_e32 v192, v192, v193
	v_add_f32_e32 v194, v194, v195
	v_add_f32_e32 v188, v188, v190
	v_add_f32_e32 v192, v192, v194
	v_add_f32_e32 v188, v188, v192
	v_add_f32_e32 v225, v225, v188
	v_exp_f32_e32 v196, v196
	v_exp_f32_e32 v197, v197
	v_exp_f32_e32 v198, v198
	v_exp_f32_e32 v199, v199
	v_mfma_f32_16x16x32_bf16 v[112:115], v[16:19], v[246:249], v[112:115]
	v_exp_f32_e32 v200, v200
	v_exp_f32_e32 v201, v201
	v_exp_f32_e32 v202, v202
	v_exp_f32_e32 v203, v203
	v_mfma_f32_16x16x32_bf16 v[108:111], v[12:15], v[246:249], v[108:111]
	v_cvt_pk_bf16_f32 v92, v196, v197
	v_cvt_pk_bf16_f32 v93, v198, v199
	v_cvt_pk_bf16_f32 v94, v200, v201
	v_cvt_pk_bf16_f32 v95, v202, v203
	v_mfma_f32_16x16x32_bf16 v[104:107], v[8:11], v[246:249], v[104:107]
	v_add_f32_e32 v196, v196, v197
	v_add_f32_e32 v198, v198, v199
	v_add_f32_e32 v200, v200, v201
	v_add_f32_e32 v202, v202, v203
	v_mfma_f32_16x16x32_bf16 v[100:103], v[4:7], v[246:249], v[100:103]
	v_add_f32_e32 v196, v196, v198
	v_add_f32_e32 v200, v200, v202
	v_add_f32_e32 v196, v196, v200
	v_add_f32_e32 v224, v224, v196
	v_mfma_f32_16x16x32_bf16 v[128:131], v[16:19], v[92:95], v[128:131]
	v_mfma_f32_16x16x32_bf16 v[124:127], v[12:15], v[92:95], v[124:127]
	v_mfma_f32_16x16x32_bf16 v[120:123], v[8:11], v[92:95], v[120:123]
	v_mfma_f32_16x16x32_bf16 v[116:119], v[4:7], v[92:95], v[116:119]
	v_add_u32_e32 v240, 0x100, v240
	s_add_u32 s92, s92, 1
	s_add_u32 s63, s63, 1
	s_and_b32 s63, s63, 3
	s_sub_i32 s80, s92, s60
	s_sub_i32 s89, s92, s76
	s_cmp_lt_i32 s80, 0
	s_cselect_b32 s89, s92, s89
	s_max_i32 s89, s89, 0
	s_min_i32 s89, s89, 7
	s_lshr_b32 s81, s89, 1
	s_lshl_b32 s81, s81, 14
	s_add_u32 s81, s81, 0x8000
	s_and_b32 s82, s89, 1
	s_lshl_b32 s20, s82, 8
	s_add_u32 s23, s81, s20
	s_lshl_b32 s20, s82, 10
	s_add_u32 s33, s81, s20
	s_add_u32 s33, s33, 0x2000
	s_cmp_ge_i32 s80, 0
	s_cselect_b32 s20, 1, 0
	s_cmp_lt_i32 s80, s76
	s_cselect_b32 s20, s20, 0
	s_cmp_lg_u32 s20, 0
	s_cbranch_scc0 .Latt_cs24
	s_lshl_b32 s81, s63, 14
	s_add_u32 s81, s81, 0x18000
	s_lshr_b32 s20, s63, 1
	s_lshl_b32 s20, s20, 4
	s_add_u32 s81, s81, s20
	s_add_u32 s82, s81, 0x2000
	s_cmp_eq_u32 s63, 3
	s_cselect_b32 s81, s83, s81
	s_cselect_b32 s82, s77, s82
	s_add_u32 s23, s81, s97
	s_add_u32 s33, s82, s90

.Latt_F0:
	s_add_u32 s92, s92, 1
	s_add_u32 s63, s63, 1
	s_and_b32 s63, s63, 3
	s_sub_i32 s80, s92, s60
	s_sub_i32 s89, s92, s76
	s_cmp_lt_i32 s80, 0
	s_cselect_b32 s89, s92, s89
	s_max_i32 s89, s89, 0
	s_min_i32 s89, s89, 7
	s_lshr_b32 s81, s89, 1
	s_lshl_b32 s81, s81, 14
	s_add_u32 s81, s81, 0x8000
	s_and_b32 s82, s89, 1
	s_lshl_b32 s20, s82, 8
	s_add_u32 s23, s81, s20
	s_lshl_b32 s20, s82, 10
	s_add_u32 s33, s81, s20
	s_add_u32 s33, s33, 0x2000
	s_cmp_ge_i32 s80, 0
	s_cselect_b32 s20, 1, 0
	s_cmp_lt_i32 s80, s76
	s_cselect_b32 s20, s20, 0
	s_cmp_lg_u32 s20, 0
	s_cbranch_scc0 .Latt_cs26
	s_lshl_b32 s81, s63, 14
	s_add_u32 s81, s81, 0x18000
	s_lshr_b32 s20, s63, 1
	s_lshl_b32 s20, s20, 4
	s_add_u32 s81, s81, s20
	s_add_u32 s82, s81, 0x2000
	s_cmp_eq_u32 s63, 3
	s_cselect_b32 s81, s83, s81
	s_cselect_b32 s82, s77, s82
	s_add_u32 s23, s81, s97
	s_add_u32 s33, s82, s90

.Latt_cs32:
	s_waitcnt lgkmcnt(0)
	v_add_u32_e32 v251, s23, v233
	v_add_u32_e32 v253, s33, v234
	ds_read_b128 v[176:179], v251 offset:0
	ds_read_b128 v[168:171], v251 offset:4096
	ds_read_b128 v[172:175], v251 offset:2048
	ds_read_b128 v[164:167], v251 offset:6144
	ds_read_b128 v[32:35], v253 offset:0
	ds_read_b128 v[28:31], v253 offset:2048
	ds_read_b128 v[24:27], v253 offset:4096
	ds_read_b128 v[20:23], v253 offset:6144
	v_mfma_f32_16x16x32_bf16 v[188:191], v[48:51], v[156:159], v[204:207]
	v_mfma_f32_16x16x32_bf16 v[192:195], v[40:43], v[156:159], v[208:211]
	v_mfma_f32_16x16x32_bf16 v[188:191], v[44:47], v[160:163], v[188:191]
	v_mfma_f32_16x16x32_bf16 v[192:195], v[36:39], v[160:163], v[192:195]
	ds_read2_b32 v[204:205], v240 offset0:0 offset1:1
	ds_read2_b32 v[206:207], v240 offset0:2 offset1:3
	ds_read2_b32 v[208:209], v240 offset0:4 offset1:5
	ds_read2_b32 v[210:211], v240 offset0:6 offset1:7
	v_mfma_f32_16x16x32_bf16 v[196:199], v[48:51], v[148:151], v[212:215]
	v_mfma_f32_16x16x32_bf16 v[200:203], v[40:43], v[148:151], v[242:245]
	v_mfma_f32_16x16x32_bf16 v[196:199], v[44:47], v[152:155], v[196:199]
	v_mfma_f32_16x16x32_bf16 v[200:203], v[36:39], v[152:155], v[200:203]
	v_exp_f32_e32 v188, v188
	v_exp_f32_e32 v189, v189
	v_exp_f32_e32 v190, v190
	v_exp_f32_e32 v191, v191
	v_exp_f32_e32 v192, v192
	v_exp_f32_e32 v193, v193
	v_exp_f32_e32 v194, v194
	v_exp_f32_e32 v195, v195
	v_cvt_pk_bf16_f32 v246, v188, v189
	v_cvt_pk_bf16_f32 v247, v190, v191
	v_cvt_pk_bf16_f32 v248, v192, v193
	v_cvt_pk_bf16_f32 v249, v194, v195
	v_add_f32_e32 v188, v188, v189
	v_add_f32_e32 v190, v190, v191
	v_add_f32_e32 v192, v192, v193
	v_add_f32_e32 v194, v194, v195
	v_add_f32_e32 v188, v188, v190
	v_add_f32_e32 v192, v192, v194
	v_add_f32_e32 v188, v188, v192
	v_add_f32_e32 v225, v225, v188
	v_mfma_f32_16x16x32_bf16 v[188:191], v[48:51], v[140:143], v[180:183]
	v_mfma_f32_16x16x32_bf16 v[192:195], v[40:43], v[140:143], v[184:187]
	v_mfma_f32_16x16x32_bf16 v[188:191], v[44:47], v[144:147], v[188:191]
	v_mfma_f32_16x16x32_bf16 v[192:195], v[36:39], v[144:147], v[192:195]
	v_exp_f32_e32 v196, v196
	v_exp_f32_e32 v197, v197
	v_exp_f32_e32 v198, v198
	v_exp_f32_e32 v199, v199
	v_mfma_f32_16x16x32_bf16 v[112:115], v[16:19], v[246:249], v[112:115]
	v_exp_f32_e32 v200, v200
	v_exp_f32_e32 v201, v201
	v_exp_f32_e32 v202, v202
	v_exp_f32_e32 v203, v203
	v_mfma_f32_16x16x32_bf16 v[108:111], v[12:15], v[246:249], v[108:111]
	v_cvt_pk_bf16_f32 v92, v196, v197
	v_cvt_pk_bf16_f32 v93, v198, v199
	v_cvt_pk_bf16_f32 v94, v200, v201
	v_cvt_pk_bf16_f32 v95, v202, v203
	v_mfma_f32_16x16x32_bf16 v[104:107], v[8:11], v[246:249], v[104:107]
	v_add_f32_e32 v196, v196, v197
	v_add_f32_e32 v198, v198, v199
	v_add_f32_e32 v200, v200, v201
	v_add_f32_e32 v202, v202, v203
	v_mfma_f32_16x16x32_bf16 v[100:103], v[4:7], v[246:249], v[100:103]
	v_add_f32_e32 v196, v196, v198
	v_add_f32_e32 v200, v200, v202
	v_add_f32_e32 v196, v196, v200
	v_add_f32_e32 v224, v224, v196
	v_mfma_f32_16x16x32_bf16 v[196:199], v[48:51], v[132:135], v[80:83]
	v_mfma_f32_16x16x32_bf16 v[200:203], v[40:43], v[132:135], v[84:87]
	v_mfma_f32_16x16x32_bf16 v[196:199], v[44:47], v[136:139], v[196:199]
	v_mfma_f32_16x16x32_bf16 v[200:203], v[36:39], v[136:139], v[200:203]
	v_exp_f32_e32 v188, v188
	v_exp_f32_e32 v189, v189
	v_exp_f32_e32 v190, v190
	v_exp_f32_e32 v191, v191
	v_mfma_f32_16x16x32_bf16 v[128:131], v[16:19], v[92:95], v[128:131]
	v_exp_f32_e32 v192, v192
	v_exp_f32_e32 v193, v193
	v_exp_f32_e32 v194, v194
	v_exp_f32_e32 v195, v195
	v_mfma_f32_16x16x32_bf16 v[124:127], v[12:15], v[92:95], v[124:127]
	v_cvt_pk_bf16_f32 v246, v188, v189
	v_cvt_pk_bf16_f32 v247, v190, v191
	v_cvt_pk_bf16_f32 v248, v192, v193
	v_cvt_pk_bf16_f32 v249, v194, v195
	v_mfma_f32_16x16x32_bf16 v[120:123], v[8:11], v[92:95], v[120:123]
	v_add_f32_e32 v188, v188, v189
	v_add_f32_e32 v190, v190, v191
	v_add_f32_e32 v192, v192, v193
	v_add_f32_e32 v194, v194, v195
	v_mfma_f32_16x16x32_bf16 v[116:119], v[4:7], v[92:95], v[116:119]
	v_add_f32_e32 v188, v188, v190
	v_add_f32_e32 v192, v192, v194
	v_add_f32_e32 v188, v188, v192
	v_add_f32_e32 v223, v223, v188
	v_exp_f32_e32 v196, v196
	v_exp_f32_e32 v197, v197
	v_exp_f32_e32 v198, v198
	v_exp_f32_e32 v199, v199
	v_mfma_f32_16x16x32_bf16 v[64:67], v[16:19], v[246:249], v[64:67]
	v_exp_f32_e32 v200, v200
	v_exp_f32_e32 v201, v201
	v_exp_f32_e32 v202, v202
	v_exp_f32_e32 v203, v203
	v_mfma_f32_16x16x32_bf16 v[60:63], v[12:15], v[246:249], v[60:63]
	v_cvt_pk_bf16_f32 v92, v196, v197
	v_cvt_pk_bf16_f32 v93, v198, v199
	v_cvt_pk_bf16_f32 v94, v200, v201
	v_cvt_pk_bf16_f32 v95, v202, v203
	v_mfma_f32_16x16x32_bf16 v[56:59], v[8:11], v[246:249], v[56:59]
	v_add_f32_e32 v196, v196, v197
	v_add_f32_e32 v198, v198, v199
	v_add_f32_e32 v200, v200, v201
	v_add_f32_e32 v202, v202, v203
	v_mfma_f32_16x16x32_bf16 v[52:55], v[4:7], v[246:249], v[52:55]
	v_add_f32_e32 v196, v196, v198
	v_add_f32_e32 v200, v200, v202
	v_add_f32_e32 v196, v196, v200
	v_add_f32_e32 v222, v222, v196
	s_waitcnt lgkmcnt(0)
	v_sub_f32_e32 v204, v204, v239
	v_sub_f32_e32 v205, v205, v239
	v_sub_f32_e32 v206, v206, v239
	v_mfma_f32_16x16x32_bf16 v[96:99], v[16:19], v[92:95], v[96:99]
	v_sub_f32_e32 v207, v207, v239
	v_sub_f32_e32 v208, v208, v239
	v_sub_f32_e32 v209, v209, v239
	v_mfma_f32_16x16x32_bf16 v[88:91], v[12:15], v[92:95], v[88:91]
	v_sub_f32_e32 v210, v210, v239
	v_sub_f32_e32 v211, v211, v239
	v_cndmask_b32_e64 v204, v238, v204, s[0:1]
	v_mfma_f32_16x16x32_bf16 v[72:75], v[8:11], v[92:95], v[72:75]
	v_cndmask_b32_e64 v205, v238, v205, s[6:7]
	v_cndmask_b32_e64 v206, v238, v206, s[8:9]
	v_cndmask_b32_e64 v207, v238, v207, s[10:11]
	v_mfma_f32_16x16x32_bf16 v[68:71], v[4:7], v[92:95], v[68:71]
	v_cndmask_b32_e64 v208, v238, v208, s[12:13]
	v_cndmask_b32_e64 v209, v238, v209, s[14:15]
	v_cndmask_b32_e64 v210, v238, v210, s[16:17]
	v_cndmask_b32_e64 v211, v238, v211, s[18:19]
	v_add_u32_e32 v240, 0x100, v240
	s_sub_u32 s91, s91, 1
	s_cmp_lg_u32 s91, 0
	s_cbranch_scc1 .Latt_F0
	s_sub_u32 s91, 8, s60

.Latt_cs36:
	s_waitcnt lgkmcnt(0)
	v_add_u32_e32 v251, s23, v233
	v_add_u32_e32 v253, s33, v234
	ds_read_b128 v[176:179], v251 offset:0
	ds_read_b128 v[168:171], v251 offset:4096
	ds_read_b128 v[172:175], v251 offset:2048
	ds_read_b128 v[164:167], v251 offset:6144
	ds_read_b128 v[32:35], v253 offset:0
	ds_read_b128 v[28:31], v253 offset:2048
	ds_read_b128 v[24:27], v253 offset:4096
	ds_read_b128 v[20:23], v253 offset:6144
	v_mfma_f32_16x16x32_bf16 v[188:191], v[48:51], v[132:135], v[76:79]
	v_mfma_f32_16x16x32_bf16 v[192:195], v[40:43], v[132:135], v[76:79]
	v_mfma_f32_16x16x32_bf16 v[188:191], v[44:47], v[136:139], v[188:191]
	v_mfma_f32_16x16x32_bf16 v[192:195], v[36:39], v[136:139], v[192:195]
	v_mfma_f32_16x16x32_bf16 v[196:199], v[48:51], v[140:143], v[76:79]
	v_mfma_f32_16x16x32_bf16 v[200:203], v[40:43], v[140:143], v[76:79]
	v_mfma_f32_16x16x32_bf16 v[196:199], v[44:47], v[144:147], v[196:199]
	v_mfma_f32_16x16x32_bf16 v[200:203], v[36:39], v[144:147], v[200:203]
	s_nop 2
	v_exp_f32_e32 v188, v188
	v_exp_f32_e32 v189, v189
	v_exp_f32_e32 v190, v190
	v_exp_f32_e32 v191, v191
	v_exp_f32_e32 v192, v192
	v_exp_f32_e32 v193, v193
	v_exp_f32_e32 v194, v194
	v_exp_f32_e32 v195, v195
	v_cvt_pk_bf16_f32 v246, v188, v189
	v_cvt_pk_bf16_f32 v247, v190, v191
	v_cvt_pk_bf16_f32 v248, v192, v193
	v_cvt_pk_bf16_f32 v249, v194, v195
	v_add_f32_e32 v188, v188, v189
	v_add_f32_e32 v190, v190, v191
	v_add_f32_e32 v192, v192, v193
	v_add_f32_e32 v194, v194, v195
	v_add_f32_e32 v188, v188, v190
	v_add_f32_e32 v192, v192, v194
	v_add_f32_e32 v188, v188, v192
	v_add_f32_e32 v222, v222, v188
	v_mfma_f32_16x16x32_bf16 v[188:191], v[48:51], v[148:151], v[76:79]
	v_mfma_f32_16x16x32_bf16 v[192:195], v[40:43], v[148:151], v[76:79]
	v_mfma_f32_16x16x32_bf16 v[188:191], v[44:47], v[152:155], v[188:191]
	v_mfma_f32_16x16x32_bf16 v[192:195], v[36:39], v[152:155], v[192:195]
	v_exp_f32_e32 v196, v196
	v_exp_f32_e32 v197, v197
	v_exp_f32_e32 v198, v198
	v_exp_f32_e32 v199, v199
	v_mfma_f32_16x16x32_bf16 v[96:99], v[16:19], v[246:249], v[96:99]
	v_exp_f32_e32 v200, v200
	v_exp_f32_e32 v201, v201
	v_exp_f32_e32 v202, v202
	v_exp_f32_e32 v203, v203
	v_mfma_f32_16x16x32_bf16 v[88:91], v[12:15], v[246:249], v[88:91]
	v_cvt_pk_bf16_f32 v92, v196, v197
	v_cvt_pk_bf16_f32 v93, v198, v199
	v_cvt_pk_bf16_f32 v94, v200, v201
	v_cvt_pk_bf16_f32 v95, v202, v203
	v_mfma_f32_16x16x32_bf16 v[72:75], v[8:11], v[246:249], v[72:75]
	v_add_f32_e32 v196, v196, v197
	v_add_f32_e32 v198, v198, v199
	v_add_f32_e32 v200, v200, v201
	v_add_f32_e32 v202, v202, v203
	v_mfma_f32_16x16x32_bf16 v[68:71], v[4:7], v[246:249], v[68:71]
	v_add_f32_e32 v196, v196, v198
	v_add_f32_e32 v200, v200, v202
	v_add_f32_e32 v196, v196, v200
	v_add_f32_e32 v223, v223, v196
	v_mfma_f32_16x16x32_bf16 v[196:199], v[48:51], v[156:159], v[76:79]
	v_mfma_f32_16x16x32_bf16 v[200:203], v[40:43], v[156:159], v[76:79]
	v_mfma_f32_16x16x32_bf16 v[196:199], v[44:47], v[160:163], v[196:199]
	v_mfma_f32_16x16x32_bf16 v[200:203], v[36:39], v[160:163], v[200:203]
	v_exp_f32_e32 v188, v188
	v_exp_f32_e32 v189, v189
	v_exp_f32_e32 v190, v190
	v_exp_f32_e32 v191, v191
	v_mfma_f32_16x16x32_bf16 v[64:67], v[16:19], v[92:95], v[64:67]
	v_exp_f32_e32 v192, v192
	v_exp_f32_e32 v193, v193
	v_exp_f32_e32 v194, v194
	v_exp_f32_e32 v195, v195
	v_mfma_f32_16x16x32_bf16 v[60:63], v[12:15], v[92:95], v[60:63]
	v_cvt_pk_bf16_f32 v246, v188, v189
	v_cvt_pk_bf16_f32 v247, v190, v191
	v_cvt_pk_bf16_f32 v248, v192, v193
	v_cvt_pk_bf16_f32 v249, v194, v195
	v_mfma_f32_16x16x32_bf16 v[56:59], v[8:11], v[92:95], v[56:59]
	v_add_f32_e32 v188, v188, v189
	v_add_f32_e32 v190, v190, v191
	v_add_f32_e32 v192, v192, v193
	v_add_f32_e32 v194, v194, v195
	v_mfma_f32_16x16x32_bf16 v[52:55], v[4:7], v[92:95], v[52:55]
	v_add_f32_e32 v188, v188, v190
	v_add_f32_e32 v192, v192, v194
	v_add_f32_e32 v188, v188, v192
	v_add_f32_e32 v224, v224, v188
	v_exp_f32_e32 v196, v196
	v_exp_f32_e32 v197, v197
	v_exp_f32_e32 v198, v198
	v_exp_f32_e32 v199, v199
	v_mfma_f32_16x16x32_bf16 v[128:131], v[16:19], v[246:249], v[128:131]
	v_exp_f32_e32 v200, v200
	v_exp_f32_e32 v201, v201
	v_exp_f32_e32 v202, v202
	v_exp_f32_e32 v203, v203
	v_mfma_f32_16x16x32_bf16 v[124:127], v[12:15], v[246:249], v[124:127]
	v_cvt_pk_bf16_f32 v92, v196, v197
	v_cvt_pk_bf16_f32 v93, v198, v199
	v_cvt_pk_bf16_f32 v94, v200, v201
	v_cvt_pk_bf16_f32 v95, v202, v203
	v_mfma_f32_16x16x32_bf16 v[120:123], v[8:11], v[246:249], v[120:123]
	v_add_f32_e32 v196, v196, v197
	v_add_f32_e32 v198, v198, v199
	v_add_f32_e32 v200, v200, v201
	v_add_f32_e32 v202, v202, v203
	v_mfma_f32_16x16x32_bf16 v[116:119], v[4:7], v[246:249], v[116:119]
	v_add_f32_e32 v196, v196, v198
	v_add_f32_e32 v200, v200, v202
	v_add_f32_e32 v196, v196, v200
	v_add_f32_e32 v225, v225, v196
	v_mfma_f32_16x16x32_bf16 v[112:115], v[16:19], v[92:95], v[112:115]
	v_mfma_f32_16x16x32_bf16 v[108:111], v[12:15], v[92:95], v[108:111]
	v_mfma_f32_16x16x32_bf16 v[104:107], v[8:11], v[92:95], v[104:107]
	v_mfma_f32_16x16x32_bf16 v[100:103], v[4:7], v[92:95], v[100:103]
	s_sub_u32 s91, s91, 1
	s_cmp_lg_u32 s91, 0
	s_cbranch_scc1 .Latt_CA
.Latt_cdone:
	s_nop 7
	s_cmp_eq_u32 s85, 1
	s_cbranch_scc1 .Latt_went
	s_cmp_eq_u32 s76, 8
	s_cbranch_scc0 .Latt_end
	s_add_u32 s92, s92, 1
	s_add_u32 s63, s63, 1
	s_and_b32 s63, s63, 3
	s_sub_i32 s80, s92, s60
	s_sub_i32 s89, s92, s76
	s_cmp_lt_i32 s80, 0
	s_cselect_b32 s89, s92, s89
	s_max_i32 s89, s89, 0
	s_min_i32 s89, s89, 7
	s_lshr_b32 s81, s89, 1
	s_lshl_b32 s81, s81, 14
	s_add_u32 s81, s81, 0x8000
	s_and_b32 s82, s89, 1
	s_lshl_b32 s20, s82, 8
	s_add_u32 s23, s81, s20
	s_lshl_b32 s20, s82, 10
	s_add_u32 s33, s81, s20
	s_add_u32 s33, s33, 0x2000
	s_cmp_ge_i32 s80, 0
	s_cselect_b32 s20, 1, 0
	s_cmp_lt_i32 s80, s76
	s_cselect_b32 s20, s20, 0
	s_cmp_lg_u32 s20, 0
	s_cbranch_scc0 .Latt_cs38
	s_lshl_b32 s81, s63, 14
	s_add_u32 s81, s81, 0x18000
	s_lshr_b32 s20, s63, 1
	s_lshl_b32 s20, s20, 4
	s_add_u32 s81, s81, s20
	s_add_u32 s82, s81, 0x2000
	s_cmp_eq_u32 s63, 3
	s_cselect_b32 s81, s83, s81
	s_cselect_b32 s82, s77, s82
	s_add_u32 s23, s81, s97
	s_add_u32 s33, s82, s90

.Latt_cs40:
	s_waitcnt lgkmcnt(0)
	s_add_u32 s92, s92, 1
	s_add_u32 s63, s63, 1
	s_and_b32 s63, s63, 3
	s_sub_i32 s80, s92, s60
	s_sub_i32 s89, s92, s76
	s_cmp_lt_i32 s80, 0
	s_cselect_b32 s89, s92, s89
	s_max_i32 s89, s89, 0
	s_min_i32 s89, s89, 7
	s_lshr_b32 s81, s89, 1
	s_lshl_b32 s81, s81, 14
	s_add_u32 s81, s81, 0x8000
	s_and_b32 s82, s89, 1
	s_lshl_b32 s20, s82, 8
	s_add_u32 s23, s81, s20
	s_lshl_b32 s20, s82, 10
	s_add_u32 s33, s81, s20
	s_add_u32 s33, s33, 0x2000
	s_cmp_ge_i32 s80, 0
	s_cselect_b32 s20, 1, 0
	s_cmp_lt_i32 s80, s76
	s_cselect_b32 s20, s20, 0
	s_cmp_lg_u32 s20, 0
	s_cbranch_scc0 .Latt_cs42
	s_lshl_b32 s81, s63, 14
	s_add_u32 s81, s81, 0x18000
	s_lshr_b32 s20, s63, 1
	s_lshl_b32 s20, s20, 4
	s_add_u32 s81, s81, s20
	s_add_u32 s82, s81, 0x2000
	s_cmp_eq_u32 s63, 3
	s_cselect_b32 s81, s83, s81
	s_cselect_b32 s82, s77, s82
	s_add_u32 s23, s81, s97
	s_add_u32 s33, s82, s90
